# all probe-verified small gains combined: SGPR-base GEMM DMA addressing + SWA context tiles in pairs + NA local tiles with wave = column group (shared K/V fragments, per-row unit skip)
# speedup vs baseline: 1.0012x; 1.0012x over previous
; __device__ __forceinline__ void na_local_tile(f32x4 (&O)[4][4], float (&ls)[4], const bf16x8 (&qf)[4][2], float negb,
;                                               const LAS unsigned char* Kt, const LAS unsigned char* Vt, int lane, const LAS float* bias_row, bool rowvalid) {
;     const int l15 = lane & 15, g = lane >> 4, q4 = l15 >> 2;
;     const LAS unsigned char* kb0 = Kt + l15 * 128;
;     const int kx0 = ((g) ^ (l15 & 7)) << 4, kx1 = ((4 + g) ^ (l15 & 7)) << 4;
;     const LAS unsigned char* vrow = Vt + (4 * g + q4) * 128 + (lane & 3) * 8;
;     const int swz = (2 * (g & 1) + (q4 >> 1)) & 3;
; #pragma unroll
;     for (int grp = 0; grp < 4; ++grp) {
; __device__ __forceinline__ void na_phase(LAS unsigned char* lds, const bf16_t* Q, const bf16_t* K, const bf16_t* V, bf16_t* Ob, const float* rpb, float negb) {
;     ...
;         if (!isctx) { b = item >> 8; hp = (item >> 5) & 7; rq = item & 31; } else { const int j = item - NA_ITEMS_LAT; b = j >> 3; hp = j & 7; rq = 0; }
;         const int hh = w >> 2, head = 2 * hp + hh;
;         const size_t ctx0 = (size_t)(MLAT + b * NCTX), lat0 = (size_t)(b * SEQ);
;         const int kr_lo = min(max(4 * rq - 4, 0), 120), kr_hi = min(max(4 * rq - 1, 0), 120) + 8;
;         const int NT = 4 + (isctx ? 0 : kr_hi - kr_lo);
;         const DmaLane dl = dma_lane(DM, hp * 128, w, lane);
;     ...
;         dma_tile<2>(lds, K, V, NA_ROW0(0), DM, dl, w);
;         dma_tile<2>(lds + NA_BUF, K, V, NA_ROW0(1), DM, dl, w);
;         dma_tile<2>(lds + 2 * NA_BUF, K, V, NA_ROW0(2), DM, dl, w);
;         for (int i = tid; i < 2 * 465; i += 512) { const int h2 = i / 465, e = i - h2 * 465; tab[h2 * 512 + e] = rpb[(2 * hp + h2) * 465 + e] * LOG2E; }
;         const int r = 4 * rq + (w & 3);
;         const size_t qrow0 = isctx ? (size_t)(MLAT + b * NCTX + (w & 3) * 64) : (size_t)(b * SEQ + r * 64);
;         bf16x8 qf[4][2];
; #pragma unroll
;         for (int grp = 0; grp < 4; ++grp)
; #pragma unroll
;             for (int ds = 0; ds < 2; ++ds) qf[grp][ds] = *(const bf16x8*)(Q + (qrow0 + 16 * grp + l15) * DM + head * 64 + 32 * ds + 8 * g);
;         f32x4 O[4][4]; float ls[4];
; #pragma unroll
;         for (int grp = 0; grp < 4; ++grp) { ls[grp] = 0.f;
; #pragma unroll
;             for (int db = 0; db < 4; ++db) O[grp][db] = (f32x4){0.f, 0.f, 0.f, 0.f}; }
;         const int r0w = min(max(r - 4, 0), 120);
.LBB0_359:
	s_and_b64 vcc, exec, s[0:1]
	s_cbranch_vccz .LBB0_450
	v_readlane_b32 s0, v241, 50
	v_readlane_b32 s1, v241, 51
	v_readlane_b32 s98, v240, 58
	v_readlane_b32 s99, v240, 59
	v_mov_b32_e32 v108, s98
	v_mov_b32_e32 v109, s99
	v_mov_b32_e32 v198, v152
	v_mov_b32_e32 v111, v155
	s_mov_b32 s92, 0
	s_nop 0
	global_load_dword v0, v155, s[0:1]
	s_waitcnt vmcnt(0)
	v_xor_b32_e32 v0, 0x80000000, v0
	v_bfe_u32 v1, v198, 3, 3
	v_xor_b32_e32 v5, v1, v198
	v_and_b32_e32 v6, 1, v198
	v_bfe_u32 v7, v198, 3, 1
	v_bfe_u32 v4, v198, 4, 2
	v_and_b32_e32 v2, 7, v198
	v_bitop3_b32 v3, v1, v198, 7 bitop3:0x78
	v_and_or_b32 v5, v5, 6, v6
	v_and_or_b32 v8, v1, 2, v7
	v_readfirstlane_b32 s0, v198
	v_lshlrev_b32_e32 v201, 4, v3
	v_lshlrev_b32_e32 v202, 4, v5
	v_lshlrev_b32_e32 v154, 3, v4
	v_bitop3_b32 v3, v4, v198, 7 bitop3:0x78
	v_bitop3_b32 v2, v4, v2, 4 bitop3:0x36
	v_lshlrev_b32_e32 v5, 9, v4
	v_lshlrev_b32_e32 v206, 5, v8
	v_bfe_u32 v8, v198, 2, 2
	v_lshlrev_b32_e32 v4, 2, v4
	s_ashr_i32 s1, s0, 6
	v_and_b32_e32 v199, 15, v198
	s_ashr_i32 s6, s0, 8
	s_movk_i32 s0, 0x3a2
	v_or_b32_e32 v8, v4, v8
	v_cmp_gt_i32_e64 s[8:9], s0, v198
	v_lshlrev_b32_e32 v210, 7, v8
	v_sub_u32_e64 v8, v199, 8 clamp
	v_writelane_b32 v240, s8, 46
	s_and_b32 s2, s1, 3
	v_sub_u32_e32 v8, v4, v8
	v_lshlrev_b32_e32 v6, 11, v1
	v_writelane_b32 v240, s9, 47
	s_lshl_b32 s0, s2, 4
	v_add_u32_e32 v10, 1, v8
	v_lshl_or_b32 v200, s1, 14, v6
	s_lshl_b32 s63, s1, 10
	v_writelane_b32 v240, s0, 48
	v_readlane_b32 s0, v241, 37
	v_cmp_gt_u32_e64 s[10:11], 16, v10
	v_add_u32_e32 v10, 2, v8
	v_and_b32_e32 v110, 48, v198
	v_readlane_b32 s1, v241, 38
	v_cmp_gt_u32_e64 s[12:13], 16, v10
	v_add_u32_e32 v10, 3, v8
	v_lshl_add_u64 v[112:113], s[0:1], 0, v[110:111]
	s_lshl_b32 s0, s6, 13
	v_writelane_b32 v240, s6, 49
	s_lshl_b32 s1, s6, 11
	v_cmp_gt_u32_e64 s[14:15], 16, v10
	s_movk_i32 s6, 0xffef
	v_add_u32_e32 v10, 17, v8
	v_sub_u32_e32 v9, v4, v199
	v_cmp_gt_u32_e64 s[8:9], 16, v8
	v_cmp_lt_u32_e64 s[16:17], s6, v8
	v_cmp_gt_u32_e64 s[18:19], 16, v10
	v_add_u32_e32 v10, 18, v8
	v_add_u32_e32 v8, 19, v8
	v_cmp_gt_u32_e64 s[22:23], 16, v8
	v_add_u32_e32 v8, 1, v9
	v_cmp_gt_u32_e64 s[26:27], 16, v8
	v_add_u32_e32 v8, 2, v9
	v_cmp_gt_u32_e64 s[28:29], 16, v8
	v_add_u32_e32 v8, 3, v9
	v_cmp_gt_u32_e64 s[30:31], 16, v8
	v_add_u32_e32 v8, 17, v9
	v_cmp_gt_u32_e64 s[36:37], 16, v8
	v_add_u32_e32 v8, 18, v9
	v_cmp_gt_u32_e64 s[38:39], 16, v8
	v_add_u32_e32 v8, 19, v9
	v_cmp_gt_u32_e64 s[40:41], 16, v8
	v_and_or_b32 v8, v198, 63, 48
	v_cmp_gt_u32_e64 s[24:25], 16, v9
	v_cmp_lt_u32_e64 s[34:35], s6, v9
	v_add_u32_e32 v9, -8, v8
	v_min_u32_e32 v9, 48, v9
	v_sub_u32_e32 v4, v4, v9
	v_and_b32_e32 v9, -16, v4
	s_movk_i32 s6, 0xffe0
	v_cmp_gt_u32_e64 s[20:21], 16, v10
	v_cmp_eq_u32_e64 s[42:43], s6, v9
	v_add_u32_e32 v10, 33, v4
	s_movk_i32 s6, 0xffd0
	v_lshlrev_b32_e32 v204, 4, v2
	v_lshlrev_b32_e32 v2, 5, v198
	v_cmp_gt_u32_e64 s[44:45], 16, v10
	v_add_u32_e32 v10, 34, v4
	v_cmp_eq_u32_e64 s[50:51], s6, v9
	v_add_u32_e32 v9, 49, v4
	v_and_b32_e32 v6, 0x180, v2
	v_lshlrev_b32_e32 v2, 3, v198
	v_cmp_gt_u32_e64 s[46:47], 16, v10
	v_add_u32_e32 v10, 35, v4
	v_cmp_gt_u32_e64 s[52:53], 16, v9
	v_add_u32_e32 v9, 50, v4
	v_add_u32_e32 v4, 51, v4
	s_add_i32 s65, s0, 0
	v_lshlrev_b32_e32 v111, 7, v199
	v_and_b32_e32 v205, 24, v2
	v_cmp_gt_u32_e64 s[56:57], 16, v4
	v_readlane_b32 s6, v241, 43
	v_add_u32_e32 v4, s65, v5
	v_lshlrev_b32_e32 v203, 4, v3
	v_readlane_b32 s7, v241, 44
	v_add3_u32 v212, v4, v6, v205
	v_or_b32_e32 v4, s0, v111
	v_cmp_gt_u32_e64 s[54:55], 16, v9
	v_lshl_add_u64 v[114:115], s[6:7], 0, v[154:155]
	v_or_b32_e32 v9, v4, v204
	s_add_i32 s6, 0, 0x8000
	v_or_b32_e32 v4, v4, v203
	v_add_u32_e32 v214, s6, v4
	v_or3_b32 v4, s0, v5, v6
	v_lshlrev_b32_e32 v5, 2, v198
	v_and_or_b32 v5, v5, 64, v4
	v_lshlrev_b32_e32 v6, 5, v7
	v_xor_b32_e32 v209, 0x60, v206
	v_or3_b32 v5, v5, v6, v205
	v_xor_b32_e32 v207, 32, v206
	v_xor_b32_e32 v208, 64, v206
	v_add_u32_e32 v215, 0, v5
	v_or3_b32 v5, v4, v209, v205
	v_add_u32_e32 v216, 0, v5
	v_or3_b32 v5, v4, v208, v205
	v_or3_b32 v4, v4, v207, v205
	v_add_u32_e32 v218, 0, v4
	v_lshlrev_b32_e32 v4, 2, v8
	v_sub_u32_e32 v4, s1, v4
	v_add_u32_e32 v219, 0, v4
	v_lshlrev_b32_e32 v4, 2, v199
	v_sub_u32_e32 v4, s1, v4
	v_mov_b32_e32 v1, v0
	v_mov_b32_e32 v2, v0
	v_mov_b32_e32 v3, v0
	v_cmp_gt_u32_e64 s[48:49], 16, v10
	v_add_u32_e32 v211, s65, v111
	v_add_u32_e32 v213, s6, v9
	v_add_u32_e32 v217, 0, v5
	s_add_i32 s69, s63, 0
	v_add_u32_e32 v220, 0, v4
	s_lshl_b32 s32, s2, 3
	s_cmp_gt_u32 s2, 1
	s_cselect_b32 s98, 8, 0
	s_add_i32 s32, s32, s98
	s_lshl_b32 s32, s32, 7
	s_cmp_eq_u32 s2, 0
	s_cbranch_scc1 .Lna2_msk_done
	s_cmp_eq_u32 s2, 3
	s_cbranch_scc1 .Lna2_msk3
	s_mov_b64 s[8:9], s[24:25]
	s_mov_b64 s[10:11], s[26:27]
	s_mov_b64 s[12:13], s[28:29]
	s_mov_b64 s[14:15], s[30:31]
	s_mov_b64 s[16:17], s[34:35]
	s_mov_b64 s[18:19], s[36:37]
	s_mov_b64 s[20:21], s[38:39]
	s_mov_b64 s[22:23], s[40:41]
	s_branch .Lna2_msk_done
.Lna2_msk3:
	s_mov_b64 s[8:9], s[42:43]
	s_mov_b64 s[10:11], s[44:45]
	s_mov_b64 s[12:13], s[46:47]
	s_mov_b64 s[14:15], s[48:49]
	s_mov_b64 s[16:17], s[50:51]
	s_mov_b64 s[18:19], s[52:53]
	s_mov_b64 s[20:21], s[54:55]
	s_mov_b64 s[22:23], s[56:57]
; __device__ __forceinline__ unsigned pkbf(float lo, float hi) { f32x2_t v = {lo, hi}; bf16x2_t b = __builtin_convertvector(v, bf16x2_t); return __builtin_bit_cast(unsigned, b); }
; __device__ __forceinline__ void store_group(const f32x4 (&Og)[4], float inv, bf16_t* orow, int g) {
; #pragma unroll
;     for (int db = 0; db < 4; ++db) { u32x2 w; w.x = pkbf(Og[db][0] * inv, Og[db][1] * inv); w.y = pkbf(Og[db][2] * inv, Og[db][3] * inv);
;         *(u32x2*)(orow + 16 * db + 4 * g) = w; }
; }
; __device__ __forceinline__ void na_phase(LAS unsigned char* lds, const bf16_t* Q, const bf16_t* K, const bf16_t* V, bf16_t* Ob, const float* rpb, float negb) {
;     ...
; #pragma unroll
;         for (int grp = 0; grp < 4; ++grp) { const float lt = red_sum4(ls[grp]); store_group(O[grp], __builtin_amdgcn_rcpf(lt), Ob + (qrow0 + 16 * grp + l15) * DM + head * 64, g); }
.Lna2_msk_done:
	s_branch .LBB0_362
.LBB0_361:
	v_mov_b32_e32 v4, v126
	s_nop 1
	v_permlane16_swap_b32_e32 v126, v4
	v_add_f32_e32 v4, v126, v4
	v_mov_b32_e32 v5, v4
	s_nop 1
	v_permlane32_swap_b32_e32 v4, v5
	v_add_f32_e32 v4, v4, v5
	v_rcp_f32_e32 v4, v4
	v_lshl_add_u64 v[6:7], s[0:1], 1, v[114:115]
	v_lshl_add_u64 v[8:9], v[6:7], 0, v[122:123]
	s_mov_b64 s[96:97], s[74:75]
	v_pk_mul_f32 v[10:11], v[48:49], v[4:5] op_sel_hi:[1,0]
	v_pk_mul_f32 v[12:13], v[50:51], v[4:5] op_sel_hi:[1,0]
	v_cvt_pk_bf16_f32 v10, v10, v11
	v_cvt_pk_bf16_f32 v11, v12, v13
	global_store_dwordx2 v[8:9], v[10:11], off
	v_pk_mul_f32 v[10:11], v[44:45], v[4:5] op_sel_hi:[1,0]
	v_pk_mul_f32 v[12:13], v[46:47], v[4:5] op_sel_hi:[1,0]
	v_cvt_pk_bf16_f32 v10, v10, v11
	v_cvt_pk_bf16_f32 v11, v12, v13
	global_store_dwordx2 v[8:9], v[10:11], off offset:32
	v_pk_mul_f32 v[10:11], v[40:41], v[4:5] op_sel_hi:[1,0]
	v_pk_mul_f32 v[12:13], v[42:43], v[4:5] op_sel_hi:[1,0]
	v_cvt_pk_bf16_f32 v10, v10, v11
	v_cvt_pk_bf16_f32 v11, v12, v13
	global_store_dwordx2 v[8:9], v[10:11], off offset:64
	v_pk_mul_f32 v[10:11], v[36:37], v[4:5] op_sel_hi:[1,0]
	v_pk_mul_f32 v[4:5], v[38:39], v[4:5] op_sel_hi:[1,0]
	v_cvt_pk_bf16_f32 v10, v10, v11
	v_mov_b32_e32 v11, v127
	s_nop 1
	v_permlane16_swap_b32_e32 v127, v11
	v_add_f32_e32 v11, v127, v11
	v_mov_b32_e32 v12, v11
	s_nop 1
	v_permlane32_swap_b32_e32 v11, v12
	v_add_f32_e32 v11, v11, v12
	v_rcp_f32_e32 v12, v11
	v_cvt_pk_bf16_f32 v11, v4, v5
	global_store_dwordx2 v[8:9], v[10:11], off offset:96
	v_lshl_add_u64 v[4:5], v[6:7], 0, v[120:121]
	v_pk_mul_f32 v[8:9], v[64:65], v[12:13] op_sel_hi:[1,0]
	v_pk_mul_f32 v[10:11], v[66:67], v[12:13] op_sel_hi:[1,0]
	v_cvt_pk_bf16_f32 v8, v8, v9
	v_cvt_pk_bf16_f32 v9, v10, v11
	global_store_dwordx2 v[4:5], v[8:9], off
	v_pk_mul_f32 v[8:9], v[60:61], v[12:13] op_sel_hi:[1,0]
	v_pk_mul_f32 v[10:11], v[62:63], v[12:13] op_sel_hi:[1,0]
	v_cvt_pk_bf16_f32 v8, v8, v9
	v_cvt_pk_bf16_f32 v9, v10, v11
	global_store_dwordx2 v[4:5], v[8:9], off offset:32
	v_pk_mul_f32 v[8:9], v[56:57], v[12:13] op_sel_hi:[1,0]
	v_pk_mul_f32 v[10:11], v[58:59], v[12:13] op_sel_hi:[1,0]
	v_cvt_pk_bf16_f32 v8, v8, v9
	v_cvt_pk_bf16_f32 v9, v10, v11
	global_store_dwordx2 v[4:5], v[8:9], off offset:64
	v_pk_mul_f32 v[8:9], v[52:53], v[12:13] op_sel_hi:[1,0]
	v_pk_mul_f32 v[10:11], v[54:55], v[12:13] op_sel_hi:[1,0]
	v_cvt_pk_bf16_f32 v8, v8, v9
	v_mov_b32_e32 v9, v124
	s_nop 1
	v_permlane16_swap_b32_e32 v124, v9
	v_add_f32_e32 v9, v124, v9
	v_mov_b32_e32 v12, v9
	s_nop 1
	v_permlane32_swap_b32_e32 v9, v12
	v_add_f32_e32 v9, v9, v12
	v_rcp_f32_e32 v12, v9
	v_cvt_pk_bf16_f32 v9, v10, v11
	global_store_dwordx2 v[4:5], v[8:9], off offset:96
	v_lshl_add_u64 v[4:5], v[6:7], 0, v[118:119]
	v_pk_mul_f32 v[8:9], v[80:81], v[12:13] op_sel_hi:[1,0]
	v_pk_mul_f32 v[10:11], v[82:83], v[12:13] op_sel_hi:[1,0]
	v_cvt_pk_bf16_f32 v8, v8, v9
	v_cvt_pk_bf16_f32 v9, v10, v11
	global_store_dwordx2 v[4:5], v[8:9], off
	v_pk_mul_f32 v[8:9], v[76:77], v[12:13] op_sel_hi:[1,0]
	v_pk_mul_f32 v[10:11], v[78:79], v[12:13] op_sel_hi:[1,0]
	v_cvt_pk_bf16_f32 v8, v8, v9
	v_cvt_pk_bf16_f32 v9, v10, v11
	global_store_dwordx2 v[4:5], v[8:9], off offset:32
	v_pk_mul_f32 v[8:9], v[72:73], v[12:13] op_sel_hi:[1,0]
	v_pk_mul_f32 v[10:11], v[74:75], v[12:13] op_sel_hi:[1,0]
	v_cvt_pk_bf16_f32 v8, v8, v9
	v_cvt_pk_bf16_f32 v9, v10, v11
	global_store_dwordx2 v[4:5], v[8:9], off offset:64
	v_pk_mul_f32 v[8:9], v[68:69], v[12:13] op_sel_hi:[1,0]
	v_pk_mul_f32 v[10:11], v[70:71], v[12:13] op_sel_hi:[1,0]
	v_cvt_pk_bf16_f32 v8, v8, v9
	v_mov_b32_e32 v9, v125
	s_nop 1
	v_permlane16_swap_b32_e32 v125, v9
	v_add_f32_e32 v9, v125, v9
	v_mov_b32_e32 v12, v9
	s_nop 1
	v_permlane32_swap_b32_e32 v9, v12
	v_add_f32_e32 v9, v9, v12
	v_rcp_f32_e32 v12, v9
	v_cvt_pk_bf16_f32 v9, v10, v11
	global_store_dwordx2 v[4:5], v[8:9], off offset:96
	v_lshl_add_u64 v[4:5], v[6:7], 0, v[116:117]
	v_pk_mul_f32 v[6:7], v[84:85], v[12:13] op_sel_hi:[1,0]
	v_pk_mul_f32 v[8:9], v[86:87], v[12:13] op_sel_hi:[1,0]
	v_cvt_pk_bf16_f32 v6, v6, v7
	v_cvt_pk_bf16_f32 v7, v8, v9
	global_store_dwordx2 v[4:5], v[6:7], off
	v_pk_mul_f32 v[6:7], v[92:93], v[12:13] op_sel_hi:[1,0]
	v_pk_mul_f32 v[8:9], v[94:95], v[12:13] op_sel_hi:[1,0]
	v_cvt_pk_bf16_f32 v6, v6, v7
	v_cvt_pk_bf16_f32 v7, v8, v9
	global_store_dwordx2 v[4:5], v[6:7], off offset:32
	v_pk_mul_f32 v[6:7], v[88:89], v[12:13] op_sel_hi:[1,0]
	v_pk_mul_f32 v[8:9], v[90:91], v[12:13] op_sel_hi:[1,0]
	v_cvt_pk_bf16_f32 v6, v6, v7
	v_cvt_pk_bf16_f32 v7, v8, v9
	global_store_dwordx2 v[4:5], v[6:7], off offset:64
	v_pk_mul_f32 v[6:7], v[96:97], v[12:13] op_sel_hi:[1,0]
	v_pk_mul_f32 v[8:9], v[98:99], v[12:13] op_sel_hi:[1,0]
	v_readlane_b32 s74, v240, 31
	s_mov_b64 s[94:95], s[72:73]
	s_mov_b64 s[72:73], s[90:91]
	s_mov_b32 s93, s33
	v_cvt_pk_bf16_f32 v6, v6, v7
	v_cvt_pk_bf16_f32 v7, v8, v9
	s_add_i32 s92, s92, 1
	s_mov_b64 s[90:91], s[78:79]
	v_readlane_b32 s75, v240, 32
	s_mov_b32 s33, s62
	global_store_dwordx2 v[4:5], v[6:7], off offset:96

; #define LAS __attribute__((address_space(3)))
; template <int NHT> __device__ __forceinline__ void dma_tile(LAS unsigned char* buf, const bf16_t* Kg, const bf16_t* Vg, size_t row0, int pitch, const DmaLane& d, int w) {
;     const unsigned char* kb = (const unsigned char*)Kg + row0 * (size_t)pitch * 2; const unsigned char* vb = (const unsigned char*)Vg + row0 * (size_t)pitch * 2;
;     const unsigned l0 = (unsigned)__builtin_amdgcn_readfirstlane((int)(unsigned)(uintptr_t)buf + w * 1024);
; #pragma unroll
;     for (int hh = 0; hh < NHT; ++hh) {
;         glds16(kb, d.koff + hh * 128, l0 + hh * 8192);
;         glds16(vb, d.voff + hh * 128, l0 + NHT * 8192 + hh * 8192); }
; }
; __device__ __forceinline__ void na_phase(LAS unsigned char* lds, const bf16_t* Q, const bf16_t* K, const bf16_t* V, bf16_t* Ob, const float* rpb, float negb) {
;     ...
;         const size_t ctx0 = (size_t)(MLAT + b * NCTX), lat0 = (size_t)(b * SEQ);
;         const int kr_lo = min(max(4 * rq - 4, 0), 120), kr_hi = min(max(4 * rq - 1, 0), 120) + 8;
;         const int NT = 4 + (isctx ? 0 : kr_hi - kr_lo);
;         const DmaLane dl = dma_lane(DM, hp * 128, w, lane);
;     ...
;         dma_tile<2>(lds, K, V, NA_ROW0(0), DM, dl, w);
;         dma_tile<2>(lds + NA_BUF, K, V, NA_ROW0(1), DM, dl, w);
;         dma_tile<2>(lds + 2 * NA_BUF, K, V, NA_ROW0(2), DM, dl, w);
;         for (int i = tid; i < 2 * 465; i += 512) { const int h2 = i / 465, e = i - h2 * 465; tab[h2 * 512 + e] = rpb[(2 * hp + h2) * 465 + e] * LOG2E; }
.LBB0_374:
	s_mov_b32 s64, s68
	s_and_b32 s7, s59, 7
	s_lshl_b32 s59, s6, 8
	s_add_i32 s82, s59, 0x8000
	s_lshl_b64 s[94:95], s[82:83], 11
	s_add_u32 s60, s67, s94
	s_addc_u32 s61, s4, s95
	v_lshl_or_b32 v4, s7, 8, v200
	s_add_u32 s96, s5, s94
	v_or_b32_e32 v221, v4, v201
	s_addc_u32 s97, s58, s95
	s_add_i32 s59, s69, 0x4000
	s_mov_b32 s66, m0
	s_mov_b32 m0, s69
	s_nop 0
	global_load_lds_dwordx4 v221, s[60:61]
	s_mov_b32 m0, s66
	v_or_b32_e32 v222, v4, v202
	s_mov_b32 s66, m0
	s_mov_b32 m0, s59
	s_nop 0
	global_load_lds_dwordx4 v222, s[96:97]
	s_mov_b32 m0, s66
	s_add_i32 s59, s69, 0x2000
	v_or_b32_e32 v223, 0x80, v221
	s_mov_b32 s66, m0
	s_mov_b32 m0, s59
	s_nop 0
	global_load_lds_dwordx4 v223, s[60:61]
	s_mov_b32 m0, s66
	s_add_i32 s59, s69, 0x6000
	v_or_b32_e32 v224, 0x80, v222
	s_mov_b32 s60, m0
	s_mov_b32 m0, s59
	s_nop 0
	global_load_lds_dwordx4 v224, s[96:97]
	s_mov_b32 m0, s60
	s_or_b32 s59, s94, 0x20000
	s_add_u32 s60, s67, s59
	s_addc_u32 s61, s4, s95
	s_add_u32 s96, s5, s59
	s_addc_u32 s97, s58, s95
	s_add_i32 s59, s69, 0x8000
	s_mov_b32 s76, m0
	s_mov_b32 m0, s59
	s_nop 0
	global_load_lds_dwordx4 v221, s[60:61]
	s_mov_b32 m0, s76
	s_add_i32 s66, s69, 0xc000
	s_mov_b32 s59, m0
	s_mov_b32 m0, s66
	s_nop 0
	global_load_lds_dwordx4 v222, s[96:97]
	s_mov_b32 m0, s59
	s_add_i32 s59, s69, 0xa000
	s_mov_b32 s66, m0
	s_mov_b32 m0, s59
	s_nop 0
	global_load_lds_dwordx4 v223, s[60:61]
	s_mov_b32 m0, s66
	s_add_i32 s59, s69, 0xe000
	s_mov_b32 s60, m0
	s_mov_b32 m0, s59
	s_nop 0
	global_load_lds_dwordx4 v224, s[96:97]
	s_mov_b32 m0, s60
	s_or_b32 s59, s94, 0x40000
	s_add_u32 s60, s67, s59
	s_addc_u32 s61, s4, s95
	s_add_u32 s96, s5, s59
	s_addc_u32 s97, s58, s95
	s_add_i32 s59, s69, 0x10000
	s_mov_b32 s76, m0
	s_mov_b32 m0, s59
	s_nop 0
	global_load_lds_dwordx4 v221, s[60:61]
	s_mov_b32 m0, s76
	s_add_i32 s66, s69, 0x14000
	s_mov_b32 s59, m0
	s_mov_b32 m0, s66
	s_nop 0
	global_load_lds_dwordx4 v222, s[96:97]
	s_mov_b32 m0, s59
	s_add_i32 s59, s69, 0x12000
	s_mov_b32 s66, m0
	s_mov_b32 m0, s59
	s_nop 0
	global_load_lds_dwordx4 v223, s[60:61]
	s_mov_b32 m0, s66
	s_add_i32 s59, s69, 0x16000
	s_mov_b32 s60, m0
	s_mov_b32 m0, s59
	s_nop 0
	global_load_lds_dwordx4 v224, s[96:97]
	s_mov_b32 m0, s60
	s_mov_b32 s62, s33
	s_mov_b64 s[96:97], exec
	v_readlane_b32 s60, v240, 46
	v_readlane_b32 s61, v240, 47
	s_and_b64 s[60:61], s[96:97], s[60:61]
	s_mov_b64 exec, s[60:61]
	s_cbranch_execz .LBB0_377
	s_mov_b64 s[60:61], 0
	v_mov_b32_e32 v4, v198

; #define LAS __attribute__((address_space(3)))
; __device__ __forceinline__ void drain_wait() { asm volatile("s_waitcnt vmcnt(0)" ::: "memory"); __syncthreads(); }
; __device__ __forceinline__ void na_phase(LAS unsigned char* lds, const bf16_t* Q, const bf16_t* K, const bf16_t* V, bf16_t* Ob, const float* rpb, float negb) {
;     ...
;         const int r = 4 * rq + (w & 3);
;         const size_t qrow0 = isctx ? (size_t)(MLAT + b * NCTX + (w & 3) * 64) : (size_t)(b * SEQ + r * 64);
;         bf16x8 qf[4][2];
; #pragma unroll
;         for (int grp = 0; grp < 4; ++grp)
; #pragma unroll
;             for (int ds = 0; ds < 2; ++ds) qf[grp][ds] = *(const bf16x8*)(Q + (qrow0 + 16 * grp + l15) * DM + head * 64 + 32 * ds + 8 * g);
;         f32x4 O[4][4]; float ls[4];
; #pragma unroll
;         for (int grp = 0; grp < 4; ++grp) { ls[grp] = 0.f;
; #pragma unroll
;             for (int db = 0; db < 4; ++db) O[grp][db] = (f32x4){0.f, 0.f, 0.f, 0.f}; }
;         const int r0w = min(max(r - 4, 0), 120);
;         drain_wait();
;         for (int t = 0; t < 4; ++t) {
;             dma_tile<2>(lds + ((t + 3) & 3) * NA_BUF, K, V, NA_ROW0(t + 3), DM, dl, w);
;             const LAS unsigned char* buf = lds + (t & 3) * NA_BUF;
;             full_tile<0, 1, 2>(O, ls, qf, negb, buf + hh * 8192, buf + 2 * 8192 + hh * 8192, lane, 0);
.LBB0_377:
	s_or_b64 exec, exec, s[96:97]
	v_sub_u32_e64 v4, s68, 1 clamp
	s_lshl_b32 s61, s6, 13
	v_readfirstlane_b32 s6, v4
	s_max_u32 s60, s68, 4
	s_min_u32 s6, s6, 0x78
	s_lshl_b32 s7, s7, 1
	v_readlane_b32 s59, v240, 49
	s_sub_i32 s6, s6, s60
	s_add_i32 s59, s7, s59
	s_add_i32 s66, s6, 16
	s_and_b64 s[6:7], exec, s[0:1]
	s_mov_b32 s33, s93
	s_cselect_b32 s93, 4, s66
	s_or_b32 s6, s68, s2
	v_readlane_b32 s7, v240, 48
	s_lshl_b32 s66, s68, 6
	s_lshl_b32 s98, s2, 4
	s_or_b32 s66, s66, s98
	s_or_b32 s7, s82, s7
	s_or_b32 s66, s61, s66
	s_and_b64 s[0:1], exec, s[0:1]
	s_cselect_b32 s0, s7, s66
	v_or_b32_e32 v154, s0, v199
	s_lshl_b32 s0, s59, 6
	s_ashr_i32 s1, s0, 31
	v_lshl_add_u64 v[28:29], s[0:1], 1, v[112:113]
	v_lshlrev_b64 v[122:123], 11, v[154:155]
	v_lshl_add_u64 v[8:9], v[28:29], 0, v[122:123]
	global_load_dwordx4 v[4:7], v[8:9], off
	s_nop 0
	global_load_dwordx4 v[8:11], v[8:9], off offset:64
	s_max_i32 s97, s6, 4
	s_or_b32 s59, s94, 0x60000
	v_or_b32_e32 v12, 64, v154
	v_mov_b32_e32 v13, v155
	v_or_b32_e32 v20, 0x80, v154
	v_mov_b32_e32 v21, v155
	v_or_b32_e32 v154, 0xc0, v154
	s_add_u32 s6, s67, s59
	v_lshlrev_b64 v[120:121], 11, v[12:13]
	v_lshlrev_b64 v[118:119], 11, v[20:21]
	v_lshlrev_b64 v[116:117], 11, v[154:155]
	s_addc_u32 s7, s4, s95
	v_lshl_add_u64 v[16:17], v[28:29], 0, v[120:121]
	v_lshl_add_u64 v[24:25], v[28:29], 0, v[118:119]
	v_lshl_add_u64 v[32:33], v[28:29], 0, v[116:117]
	s_add_u32 s94, s5, s59
	global_load_dwordx4 v[12:15], v[16:17], off
	s_nop 0
	global_load_dwordx4 v[16:19], v[16:17], off offset:64
	s_nop 0
	global_load_dwordx4 v[20:23], v[24:25], off
	s_nop 0
	global_load_dwordx4 v[24:27], v[24:25], off offset:64
	s_nop 0
	global_load_dwordx4 v[28:31], v[32:33], off
	s_nop 0
	global_load_dwordx4 v[32:35], v[32:33], off offset:64
	s_waitcnt vmcnt(0)
	s_waitcnt lgkmcnt(0)
	s_barrier
	s_addc_u32 s95, s58, s95
	s_add_i32 s59, s69, 0x18000
	s_mov_b32 s76, m0
	s_mov_b32 m0, s59
	s_nop 0
	global_load_lds_dwordx4 v221, s[6:7]
	s_mov_b32 m0, s76
	s_add_i32 s66, s69, 0x1c000
	s_mov_b32 s59, m0
	s_mov_b32 m0, s66
	s_nop 0
	global_load_lds_dwordx4 v222, s[94:95]
	s_mov_b32 m0, s59
	s_add_i32 s59, s69, 0x1a000
	s_mov_b32 s66, m0
	s_mov_b32 m0, s59
	s_nop 0
	global_load_lds_dwordx4 v223, s[6:7]
	s_mov_b32 m0, s66
	s_add_i32 s6, s69, 0x1e000
	s_mov_b32 s7, m0
	s_mov_b32 m0, s6
	s_nop 0
	global_load_lds_dwordx4 v224, s[94:95]
	s_mov_b32 m0, s7
	v_mov_b32_e32 v48, 0
	v_mov_b32_e32 v49, 0
	v_mov_b32_e32 v50, 0
	v_mov_b32_e32 v51, 0
	v_mov_b32_e32 v44, 0
	v_mov_b32_e32 v45, 0
	v_mov_b32_e32 v46, 0
	v_mov_b32_e32 v47, 0
	v_mov_b32_e32 v40, 0
	v_mov_b32_e32 v41, 0
	v_mov_b32_e32 v42, 0
	v_mov_b32_e32 v43, 0
	v_mov_b32_e32 v36, 0
	v_mov_b32_e32 v37, 0
	v_mov_b32_e32 v38, 0
	v_mov_b32_e32 v39, 0
	v_mov_b32_e32 v126, 0
	v_mov_b32_e32 v64, 0
	v_mov_b32_e32 v65, 0
	v_mov_b32_e32 v66, 0
	v_mov_b32_e32 v67, 0
	v_mov_b32_e32 v60, 0
	v_mov_b32_e32 v61, 0
	v_mov_b32_e32 v62, 0
	v_mov_b32_e32 v63, 0
	v_mov_b32_e32 v56, 0
	v_mov_b32_e32 v57, 0
	v_mov_b32_e32 v58, 0
	v_mov_b32_e32 v59, 0
	v_mov_b32_e32 v52, 0
	v_mov_b32_e32 v53, 0
	v_mov_b32_e32 v54, 0
	v_mov_b32_e32 v55, 0
	v_mov_b32_e32 v127, 0
	v_mov_b32_e32 v80, 0
	v_mov_b32_e32 v81, 0
	v_mov_b32_e32 v82, 0
	v_mov_b32_e32 v83, 0
	v_mov_b32_e32 v76, 0
	v_mov_b32_e32 v77, 0
	v_mov_b32_e32 v78, 0
	v_mov_b32_e32 v79, 0
	v_mov_b32_e32 v72, 0
	v_mov_b32_e32 v73, 0
	v_mov_b32_e32 v74, 0
	v_mov_b32_e32 v75, 0
	v_mov_b32_e32 v68, 0
	v_mov_b32_e32 v69, 0
	v_mov_b32_e32 v70, 0
	v_mov_b32_e32 v71, 0
	v_mov_b32_e32 v124, 0
	v_mov_b32_e32 v84, 0
	v_mov_b32_e32 v85, 0
	v_mov_b32_e32 v86, 0
	v_mov_b32_e32 v87, 0
	v_mov_b32_e32 v92, 0
	v_mov_b32_e32 v93, 0
	v_mov_b32_e32 v94, 0
	v_mov_b32_e32 v95, 0
	v_mov_b32_e32 v88, 0
	v_mov_b32_e32 v89, 0
	v_mov_b32_e32 v90, 0
	v_mov_b32_e32 v91, 0
	v_mov_b32_e32 v96, 0
	v_mov_b32_e32 v97, 0
	v_mov_b32_e32 v98, 0
	v_mov_b32_e32 v99, 0
	v_mov_b32_e32 v125, 0
	s_mov_b32 s96, 4
	s_lshl_b32 s6, s60, 6
	s_addk_i32 s6, 0xff00
	s_add_u32 s94, s61, s6
	s_addc_u32 s95, 0, 0
	s_mov_b32 vcc_lo, 0
	s_add_i32 s76, s65, 0
	v_add_u32_e32 v144, s76, v111
	v_add3_u32 v193, s76, v210, v205
	v_add_u32_e32 v145, v144, v204
	v_add_u32_e32 v144, v144, v203
	ds_read_b128 v[160:163], v144
	ds_read_b128 v[164:167], v145
	ds_read_b128 v[168:171], v144 offset:2048
	ds_read_b128 v[172:175], v145 offset:2048
	ds_read_b128 v[128:131], v144 offset:4096
	ds_read_b128 v[132:135], v145 offset:4096
	ds_read_b128 v[136:139], v144 offset:6144
	ds_read_b128 v[140:143], v145 offset:6144
	v_add_u32_e32 v158, v193, v206
	v_add_u32_e32 v159, v193, v207
	v_add_u32_e32 v192, v193, v208
	v_add_u32_e32 v193, v193, v209
	s_waitcnt lgkmcnt(4)
	v_mfma_f32_16x16x32_bf16 v[228:231], v[160:163], v[4:7], v[0:3]
	v_mfma_f32_16x16x32_bf16 v[232:235], v[168:171], v[4:7], v[0:3]
	v_mfma_f32_16x16x32_bf16 v[228:231], v[164:167], v[8:11], v[228:231]
	v_mfma_f32_16x16x32_bf16 v[232:235], v[172:175], v[8:11], v[232:235]
	ds_read_b64_tr_b16 v[176:177], v158 offset:16384
	ds_read_b64_tr_b16 v[178:179], v158 offset:18432
	ds_read_b64_tr_b16 v[180:181], v159 offset:16384
	ds_read_b64_tr_b16 v[182:183], v159 offset:18432
	ds_read_b64_tr_b16 v[184:185], v192 offset:16384
	ds_read_b64_tr_b16 v[186:187], v192 offset:18432
	ds_read_b64_tr_b16 v[188:189], v193 offset:16384
	ds_read_b64_tr_b16 v[190:191], v193 offset:18432
	v_mfma_f32_16x16x32_bf16 v[236:239], v[160:163], v[12:15], v[0:3]
	v_exp_f32_e32 v228, v228
	v_exp_f32_e32 v229, v229
	v_exp_f32_e32 v230, v230
	v_add_f32_e32 v154, v228, v229
	v_mfma_f32_16x16x32_bf16 v[104:107], v[168:171], v[12:15], v[0:3]
	v_exp_f32_e32 v231, v231
	v_add_f32_e32 v154, v154, v230
	v_exp_f32_e32 v232, v232
	v_add_f32_e32 v154, v154, v231
	v_mfma_f32_16x16x32_bf16 v[236:239], v[164:167], v[16:19], v[236:239]
	v_exp_f32_e32 v233, v233
	v_add_f32_e32 v154, v154, v232
	v_exp_f32_e32 v234, v234
	v_add_f32_e32 v154, v154, v233
	v_cvt_pk_bf16_f32 v228, v228, v229
	v_mfma_f32_16x16x32_bf16 v[104:107], v[172:175], v[16:19], v[104:107]
	v_exp_f32_e32 v235, v235
	v_add_f32_e32 v154, v154, v234
	v_cvt_pk_bf16_f32 v229, v230, v231
	v_cvt_pk_bf16_f32 v230, v232, v233
	v_cvt_pk_bf16_f32 v231, v234, v235
	v_add_f32_e32 v154, v154, v235
	v_add_f32_e32 v126, v126, v154
	s_waitcnt lgkmcnt(0)
; #define LAS __attribute__((address_space(3)))
; __device__ __forceinline__ s16x4 vtr(const LAS unsigned char* p) { return __builtin_bit_cast(s16x4, __builtin_amdgcn_ds_read_tr16_b64_v4i16((LAS v4i16_t*)p)); }
; __device__ __forceinline__ bf16x8 cat8(s16x4 a, s16x4 b) { return (bf16x8){a[0], a[1], a[2], a[3], b[0], b[1], b[2], b[3]}; }
; __device__ __forceinline__ bf16x8 pack8(const f32x4& a, const f32x4& b) { u32x4 w; w.x = pkbf(a[0], a[1]); w.y = pkbf(a[2], a[3]); w.z = pkbf(b[0], b[1]); w.w = pkbf(b[2], b[3]); return __builtin_bit_cast(bf16x8, w); }
;     ...
;     for (int gh = 0; gh < 4 / GPB; ++gh) {
;         f32x4 S[GPB][4];
; #pragma unroll
;         for (int kb = 0; kb < 4; ++kb) {
;             const bf16x8 kf0 = *(const LAS bf16x8*)(kb0 + (16 * kb) * 128 + kx0), kf1 = *(const LAS bf16x8*)(kb0 + (16 * kb) * 128 + kx1);
; #pragma unroll
;             for (int gi = 0; gi < GPB; ++gi) { S[gi][kb] = __builtin_amdgcn_mfma_f32_16x16x32_bf16(kf0, qf[GPB * gh + gi][0], cinit, 0, 0, 0);
;                 S[gi][kb] = __builtin_amdgcn_mfma_f32_16x16x32_bf16(kf1, qf[GPB * gh + gi][1], S[gi][kb], 0, 0, 0); } }
;         bf16x8 pf[GPB][2];
; #pragma unroll
;         for (int gi = 0; gi < GPB; ++gi) {
;             if (MASK) {
; #pragma unroll
;                 for (int kb = 0; kb < 4; ++kb)
; #pragma unroll
;                     for (int i = 0; i < 4; ++i) { const int rel = rel0 + 16 * kb + 4 * g + i; S[gi][kb][i] = ((unsigned)(rel + 128) > 256u) ? NEGBIG : S[gi][kb][i]; }
;             }
;             ls[GPB * gh + gi] += exp_step<4>(S[gi]);
;             pf[gi][0] = pack8(S[gi][0], S[gi][1]); pf[gi][1] = pack8(S[gi][2], S[gi][3]);
;         }
; #pragma unroll
;         for (int kc = 0; kc < 2; ++kc)
; #pragma unroll
;             for (int db = 0; db < 4; ++db) {
;                 const LAS unsigned char* va = vrow + ((db ^ swz) << 5) + (32 * kc) * 128;
;                 const bf16x8 vf = cat8(vtr(va), vtr(va + 16 * 128));
; #pragma unroll
;                 for (int gi = 0; gi < GPB; ++gi) O[GPB * gh + gi][db] = __builtin_amdgcn_mfma_f32_16x16x32_bf16(vf, pf[gi][kc], O[GPB * gh + gi][db], 0, 0, 0);
;             }
	v_mfma_f32_16x16x32_bf16 v[244:247], v[160:163], v[20:23], v[0:3]
	v_exp_f32_e32 v236, v236
	v_exp_f32_e32 v237, v237
	v_mfma_f32_16x16x32_bf16 v[248:251], v[168:171], v[20:23], v[0:3]
	v_exp_f32_e32 v238, v238
	v_add_f32_e32 v154, v236, v237
	v_mfma_f32_16x16x32_bf16 v[244:247], v[164:167], v[24:27], v[244:247]
	v_exp_f32_e32 v239, v239
	v_add_f32_e32 v154, v154, v238
	v_mfma_f32_16x16x32_bf16 v[248:251], v[172:175], v[24:27], v[248:251]
	v_exp_f32_e32 v104, v104
	v_add_f32_e32 v154, v154, v239
	v_mfma_f32_16x16x32_bf16 v[48:51], v[176:179], v[228:231], v[48:51]
	v_exp_f32_e32 v105, v105
	v_add_f32_e32 v154, v154, v104
	v_mfma_f32_16x16x32_bf16 v[44:47], v[180:183], v[228:231], v[44:47]
	v_exp_f32_e32 v106, v106
	v_add_f32_e32 v154, v154, v105
	v_cvt_pk_bf16_f32 v236, v236, v237
	v_mfma_f32_16x16x32_bf16 v[40:43], v[184:187], v[228:231], v[40:43]
	v_exp_f32_e32 v107, v107
	v_add_f32_e32 v154, v154, v106
	v_cvt_pk_bf16_f32 v237, v238, v239
	v_mfma_f32_16x16x32_bf16 v[36:39], v[188:191], v[228:231], v[36:39]
	v_cvt_pk_bf16_f32 v238, v104, v105
	v_cvt_pk_bf16_f32 v239, v106, v107
	v_add_f32_e32 v154, v154, v107
	v_add_f32_e32 v127, v127, v154
	v_mfma_f32_16x16x32_bf16 v[228:231], v[160:163], v[28:31], v[0:3]
	v_exp_f32_e32 v244, v244
	v_exp_f32_e32 v245, v245
	v_mfma_f32_16x16x32_bf16 v[232:235], v[168:171], v[28:31], v[0:3]
	v_exp_f32_e32 v246, v246
	v_add_f32_e32 v154, v244, v245
	v_mfma_f32_16x16x32_bf16 v[228:231], v[164:167], v[32:35], v[228:231]
	v_exp_f32_e32 v247, v247
	v_add_f32_e32 v154, v154, v246
	v_mfma_f32_16x16x32_bf16 v[232:235], v[172:175], v[32:35], v[232:235]
	v_exp_f32_e32 v248, v248
	v_add_f32_e32 v154, v154, v247
	v_mfma_f32_16x16x32_bf16 v[64:67], v[176:179], v[236:239], v[64:67]
	v_exp_f32_e32 v249, v249
	v_add_f32_e32 v154, v154, v248
	v_mfma_f32_16x16x32_bf16 v[60:63], v[180:183], v[236:239], v[60:63]
	v_exp_f32_e32 v250, v250
	v_add_f32_e32 v154, v154, v249
	v_cvt_pk_bf16_f32 v244, v244, v245
	v_mfma_f32_16x16x32_bf16 v[56:59], v[184:187], v[236:239], v[56:59]
	v_exp_f32_e32 v251, v251
	v_add_f32_e32 v154, v154, v250
	v_cvt_pk_bf16_f32 v245, v246, v247
	v_mfma_f32_16x16x32_bf16 v[52:55], v[188:191], v[236:239], v[52:55]
	v_cvt_pk_bf16_f32 v246, v248, v249
	v_cvt_pk_bf16_f32 v247, v250, v251
	v_add_f32_e32 v154, v154, v251
	v_add_f32_e32 v124, v124, v154
	ds_read_b64_tr_b16 v[160:161], v158 offset:20480
	ds_read_b64_tr_b16 v[162:163], v158 offset:22528
	ds_read_b64_tr_b16 v[164:165], v159 offset:20480
	ds_read_b64_tr_b16 v[166:167], v159 offset:22528
	ds_read_b64_tr_b16 v[168:169], v192 offset:20480
	ds_read_b64_tr_b16 v[170:171], v192 offset:22528
	ds_read_b64_tr_b16 v[172:173], v193 offset:20480
	ds_read_b64_tr_b16 v[174:175], v193 offset:22528
	v_mfma_f32_16x16x32_bf16 v[236:239], v[128:131], v[4:7], v[0:3]
	v_exp_f32_e32 v228, v228
	v_exp_f32_e32 v229, v229
	v_mfma_f32_16x16x32_bf16 v[104:107], v[136:139], v[4:7], v[0:3]
	v_exp_f32_e32 v230, v230
	v_add_f32_e32 v154, v228, v229
	v_mfma_f32_16x16x32_bf16 v[236:239], v[132:135], v[8:11], v[236:239]
	v_exp_f32_e32 v231, v231
	v_add_f32_e32 v154, v154, v230
	v_mfma_f32_16x16x32_bf16 v[104:107], v[140:143], v[8:11], v[104:107]
	v_exp_f32_e32 v232, v232
	v_add_f32_e32 v154, v154, v231
	v_mfma_f32_16x16x32_bf16 v[80:83], v[176:179], v[244:247], v[80:83]
	v_exp_f32_e32 v233, v233
	v_add_f32_e32 v154, v154, v232
	v_mfma_f32_16x16x32_bf16 v[76:79], v[180:183], v[244:247], v[76:79]
	v_exp_f32_e32 v234, v234
	v_add_f32_e32 v154, v154, v233
	v_cvt_pk_bf16_f32 v228, v228, v229
	v_mfma_f32_16x16x32_bf16 v[72:75], v[184:187], v[244:247], v[72:75]
	v_exp_f32_e32 v235, v235
	v_add_f32_e32 v154, v154, v234
	v_cvt_pk_bf16_f32 v229, v230, v231
	v_mfma_f32_16x16x32_bf16 v[68:71], v[188:191], v[244:247], v[68:71]
	v_cvt_pk_bf16_f32 v230, v232, v233
	v_cvt_pk_bf16_f32 v231, v234, v235
	v_add_f32_e32 v154, v154, v235
	v_add_f32_e32 v125, v125, v154
	v_mfma_f32_16x16x32_bf16 v[244:247], v[128:131], v[12:15], v[0:3]
	v_exp_f32_e32 v236, v236
	v_exp_f32_e32 v237, v237
	v_mfma_f32_16x16x32_bf16 v[248:251], v[136:139], v[12:15], v[0:3]
	v_exp_f32_e32 v238, v238
	v_add_f32_e32 v154, v236, v237
	v_mfma_f32_16x16x32_bf16 v[244:247], v[132:135], v[16:19], v[244:247]
	v_exp_f32_e32 v239, v239
	v_add_f32_e32 v154, v154, v238
	v_mfma_f32_16x16x32_bf16 v[248:251], v[140:143], v[16:19], v[248:251]
	v_exp_f32_e32 v104, v104
	v_add_f32_e32 v154, v154, v239
	v_mfma_f32_16x16x32_bf16 v[84:87], v[176:179], v[228:231], v[84:87]
	v_exp_f32_e32 v105, v105
	v_add_f32_e32 v154, v154, v104
	v_mfma_f32_16x16x32_bf16 v[92:95], v[180:183], v[228:231], v[92:95]
	v_exp_f32_e32 v106, v106
	v_add_f32_e32 v154, v154, v105
	v_cvt_pk_bf16_f32 v236, v236, v237
	v_mfma_f32_16x16x32_bf16 v[88:91], v[184:187], v[228:231], v[88:91]
	v_exp_f32_e32 v107, v107
	v_add_f32_e32 v154, v154, v106
	v_cvt_pk_bf16_f32 v237, v238, v239
	v_mfma_f32_16x16x32_bf16 v[96:99], v[188:191], v[228:231], v[96:99]
	v_cvt_pk_bf16_f32 v238, v104, v105
	v_cvt_pk_bf16_f32 v239, v106, v107
	v_add_f32_e32 v154, v154, v107
	v_add_f32_e32 v126, v126, v154
	s_waitcnt lgkmcnt(0)
; #define LAS __attribute__((address_space(3)))
; __device__ __forceinline__ s16x4 vtr(const LAS unsigned char* p) { return __builtin_bit_cast(s16x4, __builtin_amdgcn_ds_read_tr16_b64_v4i16((LAS v4i16_t*)p)); }
; __device__ __forceinline__ bf16x8 cat8(s16x4 a, s16x4 b) { return (bf16x8){a[0], a[1], a[2], a[3], b[0], b[1], b[2], b[3]}; }
; __device__ __forceinline__ bf16x8 pack8(const f32x4& a, const f32x4& b) { u32x4 w; w.x = pkbf(a[0], a[1]); w.y = pkbf(a[2], a[3]); w.z = pkbf(b[0], b[1]); w.w = pkbf(b[2], b[3]); return __builtin_bit_cast(bf16x8, w); }
; template <int NI> __device__ __forceinline__ void ring_wait() { asm volatile("s_waitcnt vmcnt(%0)" :: "n"(2 * NI) : "memory"); __syncthreads(); }
;     ...
;             pf[gi][0] = pack8(S[gi][0], S[gi][1]); pf[gi][1] = pack8(S[gi][2], S[gi][3]);
;         }
; #pragma unroll
;         for (int kc = 0; kc < 2; ++kc)
; #pragma unroll
;             for (int db = 0; db < 4; ++db) {
;                 const LAS unsigned char* va = vrow + ((db ^ swz) << 5) + (32 * kc) * 128;
;                 const bf16x8 vf = cat8(vtr(va), vtr(va + 16 * 128));
; #pragma unroll
;                 for (int gi = 0; gi < GPB; ++gi) O[GPB * gh + gi][db] = __builtin_amdgcn_mfma_f32_16x16x32_bf16(vf, pf[gi][kc], O[GPB * gh + gi][db], 0, 0, 0);
;             }
; __device__ __forceinline__ void na_phase(LAS unsigned char* lds, const bf16_t* Q, const bf16_t* K, const bf16_t* V, bf16_t* Ob, const float* rpb, float negb) {
;     ...
;         for (int t = 0; t < 4; ++t) {
;             dma_tile<2>(lds + ((t + 3) & 3) * NA_BUF, K, V, NA_ROW0(t + 3), DM, dl, w);
;             const LAS unsigned char* buf = lds + (t & 3) * NA_BUF;
;             full_tile<0, 1, 2>(O, ls, qf, negb, buf + hh * 8192, buf + 2 * 8192 + hh * 8192, lane, 0);
;             ring_wait<4>();
;         }
	v_mfma_f32_16x16x32_bf16 v[228:231], v[128:131], v[20:23], v[0:3]
	v_exp_f32_e32 v244, v244
	v_exp_f32_e32 v245, v245
	v_mfma_f32_16x16x32_bf16 v[232:235], v[136:139], v[20:23], v[0:3]
	v_exp_f32_e32 v246, v246
	v_add_f32_e32 v154, v244, v245
	v_mfma_f32_16x16x32_bf16 v[228:231], v[132:135], v[24:27], v[228:231]
	v_exp_f32_e32 v247, v247
	v_add_f32_e32 v154, v154, v246
	v_mfma_f32_16x16x32_bf16 v[232:235], v[140:143], v[24:27], v[232:235]
	v_exp_f32_e32 v248, v248
	v_add_f32_e32 v154, v154, v247
	v_mfma_f32_16x16x32_bf16 v[48:51], v[160:163], v[236:239], v[48:51]
	v_exp_f32_e32 v249, v249
	v_add_f32_e32 v154, v154, v248
	v_mfma_f32_16x16x32_bf16 v[44:47], v[164:167], v[236:239], v[44:47]
	v_exp_f32_e32 v250, v250
	v_add_f32_e32 v154, v154, v249
	v_cvt_pk_bf16_f32 v244, v244, v245
	v_mfma_f32_16x16x32_bf16 v[40:43], v[168:171], v[236:239], v[40:43]
	v_exp_f32_e32 v251, v251
	v_add_f32_e32 v154, v154, v250
	v_cvt_pk_bf16_f32 v245, v246, v247
	v_mfma_f32_16x16x32_bf16 v[36:39], v[172:175], v[236:239], v[36:39]
	v_cvt_pk_bf16_f32 v246, v248, v249
	v_cvt_pk_bf16_f32 v247, v250, v251
	v_add_f32_e32 v154, v154, v251
	v_add_f32_e32 v127, v127, v154
	v_mfma_f32_16x16x32_bf16 v[236:239], v[128:131], v[28:31], v[0:3]
	v_exp_f32_e32 v228, v228
	v_exp_f32_e32 v229, v229
	v_mfma_f32_16x16x32_bf16 v[104:107], v[136:139], v[28:31], v[0:3]
	v_exp_f32_e32 v230, v230
	v_add_f32_e32 v154, v228, v229
	v_mfma_f32_16x16x32_bf16 v[236:239], v[132:135], v[32:35], v[236:239]
	v_exp_f32_e32 v231, v231
	v_add_f32_e32 v154, v154, v230
	v_mfma_f32_16x16x32_bf16 v[104:107], v[140:143], v[32:35], v[104:107]
	v_exp_f32_e32 v232, v232
	v_add_f32_e32 v154, v154, v231
	v_mfma_f32_16x16x32_bf16 v[64:67], v[160:163], v[244:247], v[64:67]
	v_exp_f32_e32 v233, v233
	v_add_f32_e32 v154, v154, v232
	v_mfma_f32_16x16x32_bf16 v[60:63], v[164:167], v[244:247], v[60:63]
	v_exp_f32_e32 v234, v234
	v_add_f32_e32 v154, v154, v233
	v_cvt_pk_bf16_f32 v228, v228, v229
	v_mfma_f32_16x16x32_bf16 v[56:59], v[168:171], v[244:247], v[56:59]
	v_exp_f32_e32 v235, v235
	v_add_f32_e32 v154, v154, v234
	v_cvt_pk_bf16_f32 v229, v230, v231
	v_mfma_f32_16x16x32_bf16 v[52:55], v[172:175], v[244:247], v[52:55]
	v_cvt_pk_bf16_f32 v230, v232, v233
	v_cvt_pk_bf16_f32 v231, v234, v235
	v_add_f32_e32 v154, v154, v235
	v_add_f32_e32 v124, v124, v154
	v_mfma_f32_16x16x32_bf16 v[80:83], v[160:163], v[228:231], v[80:83]
	v_exp_f32_e32 v236, v236
	v_exp_f32_e32 v237, v237
	v_exp_f32_e32 v238, v238
	v_add_f32_e32 v154, v236, v237
	v_mfma_f32_16x16x32_bf16 v[76:79], v[164:167], v[228:231], v[76:79]
	v_exp_f32_e32 v239, v239
	v_add_f32_e32 v154, v154, v238
	v_exp_f32_e32 v104, v104
	v_add_f32_e32 v154, v154, v239
	v_mfma_f32_16x16x32_bf16 v[72:75], v[168:171], v[228:231], v[72:75]
	v_exp_f32_e32 v105, v105
	v_add_f32_e32 v154, v154, v104
	v_exp_f32_e32 v106, v106
	v_add_f32_e32 v154, v154, v105
	v_cvt_pk_bf16_f32 v236, v236, v237
	v_mfma_f32_16x16x32_bf16 v[68:71], v[172:175], v[228:231], v[68:71]
	v_exp_f32_e32 v107, v107
	v_add_f32_e32 v154, v154, v106
	v_cvt_pk_bf16_f32 v237, v238, v239
	v_cvt_pk_bf16_f32 v238, v104, v105
	v_cvt_pk_bf16_f32 v239, v106, v107
	v_add_f32_e32 v154, v154, v107
	v_add_f32_e32 v125, v125, v154
	v_mfma_f32_16x16x32_bf16 v[84:87], v[160:163], v[236:239], v[84:87]
	v_mfma_f32_16x16x32_bf16 v[92:95], v[164:167], v[236:239], v[92:95]
	v_mfma_f32_16x16x32_bf16 v[88:91], v[168:171], v[236:239], v[88:91]
	v_mfma_f32_16x16x32_bf16 v[96:99], v[172:175], v[236:239], v[96:99]
	s_waitcnt vmcnt(8)
	s_barrier
	s_cmp_lt_i32 s96, s93
	s_cselect_b32 s7, s95, 0
	s_cselect_b32 s6, s94, s82
	s_lshl_b64 s[6:7], s[6:7], 11
	s_add_u32 s76, s67, s6
	s_addc_u32 s77, s4, s7
	s_add_u32 s6, s5, s6
	s_addc_u32 s7, s58, s7
	s_add_i32 s59, s69, vcc_lo
	s_mov_b32 vcc_hi, m0
	s_mov_b32 m0, s59
	s_nop 0
	global_load_lds_dwordx4 v221, s[76:77]
	s_mov_b32 m0, vcc_hi
	s_add_i32 s66, s59, 0x4000
	s_mov_b32 vcc_hi, m0
	s_mov_b32 m0, s66
	s_nop 0
	global_load_lds_dwordx4 v222, s[6:7]
	s_mov_b32 m0, vcc_hi
	s_add_i32 s66, s59, 0x2000
	s_mov_b32 vcc_hi, m0
	s_mov_b32 m0, s66
	s_nop 0
	global_load_lds_dwordx4 v223, s[76:77]
	s_mov_b32 m0, vcc_hi
	s_addk_i32 s59, 0x6000
	s_mov_b32 s66, m0
	s_mov_b32 m0, s59
	s_nop 0
	global_load_lds_dwordx4 v224, s[6:7]
	s_mov_b32 m0, s66
	s_add_i32 s76, s65, vcc_lo
	s_add_i32 s76, s76, 0x8000
	v_add_u32_e32 v144, s76, v111
	v_add3_u32 v193, s76, v210, v205
	v_add_u32_e32 v145, v144, v204
	v_add_u32_e32 v144, v144, v203
	ds_read_b128 v[160:163], v144
	ds_read_b128 v[164:167], v145
	ds_read_b128 v[168:171], v144 offset:2048
	ds_read_b128 v[172:175], v145 offset:2048
	ds_read_b128 v[128:131], v144 offset:4096
	ds_read_b128 v[132:135], v145 offset:4096
	ds_read_b128 v[136:139], v144 offset:6144
	ds_read_b128 v[140:143], v145 offset:6144
	v_add_u32_e32 v158, v193, v206
	v_add_u32_e32 v159, v193, v207
	v_add_u32_e32 v192, v193, v208
	v_add_u32_e32 v193, v193, v209
	s_waitcnt lgkmcnt(4)
; #define LAS __attribute__((address_space(3)))
; __device__ __forceinline__ s16x4 vtr(const LAS unsigned char* p) { return __builtin_bit_cast(s16x4, __builtin_amdgcn_ds_read_tr16_b64_v4i16((LAS v4i16_t*)p)); }
; __device__ __forceinline__ bf16x8 cat8(s16x4 a, s16x4 b) { return (bf16x8){a[0], a[1], a[2], a[3], b[0], b[1], b[2], b[3]}; }
; __device__ __forceinline__ bf16x8 pack8(const f32x4& a, const f32x4& b) { u32x4 w; w.x = pkbf(a[0], a[1]); w.y = pkbf(a[2], a[3]); w.z = pkbf(b[0], b[1]); w.w = pkbf(b[2], b[3]); return __builtin_bit_cast(bf16x8, w); }
;     ...
;     for (int gh = 0; gh < 4 / GPB; ++gh) {
;         f32x4 S[GPB][4];
; #pragma unroll
;         for (int kb = 0; kb < 4; ++kb) {
;             const bf16x8 kf0 = *(const LAS bf16x8*)(kb0 + (16 * kb) * 128 + kx0), kf1 = *(const LAS bf16x8*)(kb0 + (16 * kb) * 128 + kx1);
; #pragma unroll
;             for (int gi = 0; gi < GPB; ++gi) { S[gi][kb] = __builtin_amdgcn_mfma_f32_16x16x32_bf16(kf0, qf[GPB * gh + gi][0], cinit, 0, 0, 0);
;                 S[gi][kb] = __builtin_amdgcn_mfma_f32_16x16x32_bf16(kf1, qf[GPB * gh + gi][1], S[gi][kb], 0, 0, 0); } }
;         bf16x8 pf[GPB][2];
; #pragma unroll
;         for (int gi = 0; gi < GPB; ++gi) {
;             if (MASK) {
; #pragma unroll
;                 for (int kb = 0; kb < 4; ++kb)
; #pragma unroll
;                     for (int i = 0; i < 4; ++i) { const int rel = rel0 + 16 * kb + 4 * g + i; S[gi][kb][i] = ((unsigned)(rel + 128) > 256u) ? NEGBIG : S[gi][kb][i]; }
;             }
;             ls[GPB * gh + gi] += exp_step<4>(S[gi]);
;             pf[gi][0] = pack8(S[gi][0], S[gi][1]); pf[gi][1] = pack8(S[gi][2], S[gi][3]);
;         }
; #pragma unroll
;         for (int kc = 0; kc < 2; ++kc)
; #pragma unroll
;             for (int db = 0; db < 4; ++db) {
;                 const LAS unsigned char* va = vrow + ((db ^ swz) << 5) + (32 * kc) * 128;
;                 const bf16x8 vf = cat8(vtr(va), vtr(va + 16 * 128));
; #pragma unroll
;                 for (int gi = 0; gi < GPB; ++gi) O[GPB * gh + gi][db] = __builtin_amdgcn_mfma_f32_16x16x32_bf16(vf, pf[gi][kc], O[GPB * gh + gi][db], 0, 0, 0);
;             }
	v_mfma_f32_16x16x32_bf16 v[228:231], v[160:163], v[4:7], v[0:3]
	v_mfma_f32_16x16x32_bf16 v[232:235], v[168:171], v[4:7], v[0:3]
	v_mfma_f32_16x16x32_bf16 v[228:231], v[164:167], v[8:11], v[228:231]
	v_mfma_f32_16x16x32_bf16 v[232:235], v[172:175], v[8:11], v[232:235]
	ds_read_b64_tr_b16 v[176:177], v158 offset:16384
	ds_read_b64_tr_b16 v[178:179], v158 offset:18432
	ds_read_b64_tr_b16 v[180:181], v159 offset:16384
	ds_read_b64_tr_b16 v[182:183], v159 offset:18432
	ds_read_b64_tr_b16 v[184:185], v192 offset:16384
	ds_read_b64_tr_b16 v[186:187], v192 offset:18432
	ds_read_b64_tr_b16 v[188:189], v193 offset:16384
	ds_read_b64_tr_b16 v[190:191], v193 offset:18432
	v_mfma_f32_16x16x32_bf16 v[236:239], v[160:163], v[12:15], v[0:3]
	v_exp_f32_e32 v228, v228
	v_exp_f32_e32 v229, v229
	v_exp_f32_e32 v230, v230
	v_add_f32_e32 v154, v228, v229
	v_mfma_f32_16x16x32_bf16 v[104:107], v[168:171], v[12:15], v[0:3]
	v_exp_f32_e32 v231, v231
	v_add_f32_e32 v154, v154, v230
	v_exp_f32_e32 v232, v232
	v_add_f32_e32 v154, v154, v231
	v_mfma_f32_16x16x32_bf16 v[236:239], v[164:167], v[16:19], v[236:239]
	v_exp_f32_e32 v233, v233
	v_add_f32_e32 v154, v154, v232
	v_exp_f32_e32 v234, v234
	v_add_f32_e32 v154, v154, v233
	v_cvt_pk_bf16_f32 v228, v228, v229
	v_mfma_f32_16x16x32_bf16 v[104:107], v[172:175], v[16:19], v[104:107]
	v_exp_f32_e32 v235, v235
	v_add_f32_e32 v154, v154, v234
	v_cvt_pk_bf16_f32 v229, v230, v231
	v_cvt_pk_bf16_f32 v230, v232, v233
	v_cvt_pk_bf16_f32 v231, v234, v235
	v_add_f32_e32 v154, v154, v235
	v_add_f32_e32 v126, v126, v154
	s_waitcnt lgkmcnt(0)
	v_mfma_f32_16x16x32_bf16 v[244:247], v[160:163], v[20:23], v[0:3]
	v_exp_f32_e32 v236, v236
	v_exp_f32_e32 v237, v237
	v_mfma_f32_16x16x32_bf16 v[248:251], v[168:171], v[20:23], v[0:3]
	v_exp_f32_e32 v238, v238
	v_add_f32_e32 v154, v236, v237
	v_mfma_f32_16x16x32_bf16 v[244:247], v[164:167], v[24:27], v[244:247]
	v_exp_f32_e32 v239, v239
	v_add_f32_e32 v154, v154, v238
	v_mfma_f32_16x16x32_bf16 v[248:251], v[172:175], v[24:27], v[248:251]
	v_exp_f32_e32 v104, v104
	v_add_f32_e32 v154, v154, v239
	v_mfma_f32_16x16x32_bf16 v[48:51], v[176:179], v[228:231], v[48:51]
	v_exp_f32_e32 v105, v105
	v_add_f32_e32 v154, v154, v104
	v_mfma_f32_16x16x32_bf16 v[44:47], v[180:183], v[228:231], v[44:47]
	v_exp_f32_e32 v106, v106
	v_add_f32_e32 v154, v154, v105
	v_cvt_pk_bf16_f32 v236, v236, v237
	v_mfma_f32_16x16x32_bf16 v[40:43], v[184:187], v[228:231], v[40:43]
	v_exp_f32_e32 v107, v107
	v_add_f32_e32 v154, v154, v106
	v_cvt_pk_bf16_f32 v237, v238, v239
	v_mfma_f32_16x16x32_bf16 v[36:39], v[188:191], v[228:231], v[36:39]
	v_cvt_pk_bf16_f32 v238, v104, v105
	v_cvt_pk_bf16_f32 v239, v106, v107
	v_add_f32_e32 v154, v154, v107
	v_add_f32_e32 v127, v127, v154
	v_mfma_f32_16x16x32_bf16 v[228:231], v[160:163], v[28:31], v[0:3]
	v_exp_f32_e32 v244, v244
	v_exp_f32_e32 v245, v245
	v_mfma_f32_16x16x32_bf16 v[232:235], v[168:171], v[28:31], v[0:3]
	v_exp_f32_e32 v246, v246
	v_add_f32_e32 v154, v244, v245
	v_mfma_f32_16x16x32_bf16 v[228:231], v[164:167], v[32:35], v[228:231]
	v_exp_f32_e32 v247, v247
	v_add_f32_e32 v154, v154, v246
	v_mfma_f32_16x16x32_bf16 v[232:235], v[172:175], v[32:35], v[232:235]
	v_exp_f32_e32 v248, v248
	v_add_f32_e32 v154, v154, v247
	v_mfma_f32_16x16x32_bf16 v[64:67], v[176:179], v[236:239], v[64:67]
	v_exp_f32_e32 v249, v249
	v_add_f32_e32 v154, v154, v248
	v_mfma_f32_16x16x32_bf16 v[60:63], v[180:183], v[236:239], v[60:63]
	v_exp_f32_e32 v250, v250
	v_add_f32_e32 v154, v154, v249
	v_cvt_pk_bf16_f32 v244, v244, v245
	v_mfma_f32_16x16x32_bf16 v[56:59], v[184:187], v[236:239], v[56:59]
	v_exp_f32_e32 v251, v251
	v_add_f32_e32 v154, v154, v250
	v_cvt_pk_bf16_f32 v245, v246, v247
	v_mfma_f32_16x16x32_bf16 v[52:55], v[188:191], v[236:239], v[52:55]
	v_cvt_pk_bf16_f32 v246, v248, v249
	v_cvt_pk_bf16_f32 v247, v250, v251
	v_add_f32_e32 v154, v154, v251
	v_add_f32_e32 v124, v124, v154
	ds_read_b64_tr_b16 v[160:161], v158 offset:20480
	ds_read_b64_tr_b16 v[162:163], v158 offset:22528
	ds_read_b64_tr_b16 v[164:165], v159 offset:20480
	ds_read_b64_tr_b16 v[166:167], v159 offset:22528
	ds_read_b64_tr_b16 v[168:169], v192 offset:20480
	ds_read_b64_tr_b16 v[170:171], v192 offset:22528
	ds_read_b64_tr_b16 v[172:173], v193 offset:20480
	ds_read_b64_tr_b16 v[174:175], v193 offset:22528
	v_mfma_f32_16x16x32_bf16 v[236:239], v[128:131], v[4:7], v[0:3]
	v_exp_f32_e32 v228, v228
	v_exp_f32_e32 v229, v229
	v_mfma_f32_16x16x32_bf16 v[104:107], v[136:139], v[4:7], v[0:3]
	v_exp_f32_e32 v230, v230
	v_add_f32_e32 v154, v228, v229
	v_mfma_f32_16x16x32_bf16 v[236:239], v[132:135], v[8:11], v[236:239]
	v_exp_f32_e32 v231, v231
	v_add_f32_e32 v154, v154, v230
	v_mfma_f32_16x16x32_bf16 v[104:107], v[140:143], v[8:11], v[104:107]
	v_exp_f32_e32 v232, v232
	v_add_f32_e32 v154, v154, v231
	v_mfma_f32_16x16x32_bf16 v[80:83], v[176:179], v[244:247], v[80:83]
	v_exp_f32_e32 v233, v233
	v_add_f32_e32 v154, v154, v232
	v_mfma_f32_16x16x32_bf16 v[76:79], v[180:183], v[244:247], v[76:79]
	v_exp_f32_e32 v234, v234
	v_add_f32_e32 v154, v154, v233
	v_cvt_pk_bf16_f32 v228, v228, v229
	v_mfma_f32_16x16x32_bf16 v[72:75], v[184:187], v[244:247], v[72:75]
	v_exp_f32_e32 v235, v235
	v_add_f32_e32 v154, v154, v234
	v_cvt_pk_bf16_f32 v229, v230, v231
	v_mfma_f32_16x16x32_bf16 v[68:71], v[188:191], v[244:247], v[68:71]
	v_cvt_pk_bf16_f32 v230, v232, v233
	v_cvt_pk_bf16_f32 v231, v234, v235
	v_add_f32_e32 v154, v154, v235
	v_add_f32_e32 v125, v125, v154
	v_mfma_f32_16x16x32_bf16 v[244:247], v[128:131], v[12:15], v[0:3]
	v_exp_f32_e32 v236, v236
	v_exp_f32_e32 v237, v237
	v_mfma_f32_16x16x32_bf16 v[248:251], v[136:139], v[12:15], v[0:3]
	v_exp_f32_e32 v238, v238
	v_add_f32_e32 v154, v236, v237
	v_mfma_f32_16x16x32_bf16 v[244:247], v[132:135], v[16:19], v[244:247]
	v_exp_f32_e32 v239, v239
	v_add_f32_e32 v154, v154, v238
	v_mfma_f32_16x16x32_bf16 v[248:251], v[140:143], v[16:19], v[248:251]
	v_exp_f32_e32 v104, v104
	v_add_f32_e32 v154, v154, v239
	v_mfma_f32_16x16x32_bf16 v[84:87], v[176:179], v[228:231], v[84:87]
	v_exp_f32_e32 v105, v105
	v_add_f32_e32 v154, v154, v104
	v_mfma_f32_16x16x32_bf16 v[92:95], v[180:183], v[228:231], v[92:95]
	v_exp_f32_e32 v106, v106
	v_add_f32_e32 v154, v154, v105
	v_cvt_pk_bf16_f32 v236, v236, v237
	v_mfma_f32_16x16x32_bf16 v[88:91], v[184:187], v[228:231], v[88:91]
	v_exp_f32_e32 v107, v107
	v_add_f32_e32 v154, v154, v106
	v_cvt_pk_bf16_f32 v237, v238, v239
	v_mfma_f32_16x16x32_bf16 v[96:99], v[188:191], v[228:231], v[96:99]
	v_cvt_pk_bf16_f32 v238, v104, v105
	v_cvt_pk_bf16_f32 v239, v106, v107
	v_add_f32_e32 v154, v154, v107
	v_add_f32_e32 v126, v126, v154
	s_waitcnt lgkmcnt(0)
; #define LAS __attribute__((address_space(3)))
; __device__ __forceinline__ s16x4 vtr(const LAS unsigned char* p) { return __builtin_bit_cast(s16x4, __builtin_amdgcn_ds_read_tr16_b64_v4i16((LAS v4i16_t*)p)); }
; __device__ __forceinline__ bf16x8 cat8(s16x4 a, s16x4 b) { return (bf16x8){a[0], a[1], a[2], a[3], b[0], b[1], b[2], b[3]}; }
; __device__ __forceinline__ bf16x8 pack8(const f32x4& a, const f32x4& b) { u32x4 w; w.x = pkbf(a[0], a[1]); w.y = pkbf(a[2], a[3]); w.z = pkbf(b[0], b[1]); w.w = pkbf(b[2], b[3]); return __builtin_bit_cast(bf16x8, w); }
; template <int NI> __device__ __forceinline__ void ring_wait() { asm volatile("s_waitcnt vmcnt(%0)" :: "n"(2 * NI) : "memory"); __syncthreads(); }
;     ...
;             pf[gi][0] = pack8(S[gi][0], S[gi][1]); pf[gi][1] = pack8(S[gi][2], S[gi][3]);
;         }
; #pragma unroll
;         for (int kc = 0; kc < 2; ++kc)
; #pragma unroll
;             for (int db = 0; db < 4; ++db) {
;                 const LAS unsigned char* va = vrow + ((db ^ swz) << 5) + (32 * kc) * 128;
;                 const bf16x8 vf = cat8(vtr(va), vtr(va + 16 * 128));
; #pragma unroll
;                 for (int gi = 0; gi < GPB; ++gi) O[GPB * gh + gi][db] = __builtin_amdgcn_mfma_f32_16x16x32_bf16(vf, pf[gi][kc], O[GPB * gh + gi][db], 0, 0, 0);
;             }
; __device__ __forceinline__ void na_phase(LAS unsigned char* lds, const bf16_t* Q, const bf16_t* K, const bf16_t* V, bf16_t* Ob, const float* rpb, float negb) {
;     ...
;         for (int t = 0; t < 4; ++t) {
;             dma_tile<2>(lds + ((t + 3) & 3) * NA_BUF, K, V, NA_ROW0(t + 3), DM, dl, w);
;             const LAS unsigned char* buf = lds + (t & 3) * NA_BUF;
;             full_tile<0, 1, 2>(O, ls, qf, negb, buf + hh * 8192, buf + 2 * 8192 + hh * 8192, lane, 0);
;             ring_wait<4>();
;         }
	v_mfma_f32_16x16x32_bf16 v[228:231], v[128:131], v[20:23], v[0:3]
	v_exp_f32_e32 v244, v244
	v_exp_f32_e32 v245, v245
	v_mfma_f32_16x16x32_bf16 v[232:235], v[136:139], v[20:23], v[0:3]
	v_exp_f32_e32 v246, v246
	v_add_f32_e32 v154, v244, v245
	v_mfma_f32_16x16x32_bf16 v[228:231], v[132:135], v[24:27], v[228:231]
	v_exp_f32_e32 v247, v247
	v_add_f32_e32 v154, v154, v246
	v_mfma_f32_16x16x32_bf16 v[232:235], v[140:143], v[24:27], v[232:235]
	v_exp_f32_e32 v248, v248
	v_add_f32_e32 v154, v154, v247
	v_mfma_f32_16x16x32_bf16 v[48:51], v[160:163], v[236:239], v[48:51]
	v_exp_f32_e32 v249, v249
	v_add_f32_e32 v154, v154, v248
	v_mfma_f32_16x16x32_bf16 v[44:47], v[164:167], v[236:239], v[44:47]
	v_exp_f32_e32 v250, v250
	v_add_f32_e32 v154, v154, v249
	v_cvt_pk_bf16_f32 v244, v244, v245
	v_mfma_f32_16x16x32_bf16 v[40:43], v[168:171], v[236:239], v[40:43]
	v_exp_f32_e32 v251, v251
	v_add_f32_e32 v154, v154, v250
	v_cvt_pk_bf16_f32 v245, v246, v247
	v_mfma_f32_16x16x32_bf16 v[36:39], v[172:175], v[236:239], v[36:39]
	v_cvt_pk_bf16_f32 v246, v248, v249
	v_cvt_pk_bf16_f32 v247, v250, v251
	v_add_f32_e32 v154, v154, v251
	v_add_f32_e32 v127, v127, v154
	v_mfma_f32_16x16x32_bf16 v[236:239], v[128:131], v[28:31], v[0:3]
	v_exp_f32_e32 v228, v228
	v_exp_f32_e32 v229, v229
	v_mfma_f32_16x16x32_bf16 v[104:107], v[136:139], v[28:31], v[0:3]
	v_exp_f32_e32 v230, v230
	v_add_f32_e32 v154, v228, v229
	v_mfma_f32_16x16x32_bf16 v[236:239], v[132:135], v[32:35], v[236:239]
	v_exp_f32_e32 v231, v231
	v_add_f32_e32 v154, v154, v230
	v_mfma_f32_16x16x32_bf16 v[104:107], v[140:143], v[32:35], v[104:107]
	v_exp_f32_e32 v232, v232
	v_add_f32_e32 v154, v154, v231
	v_mfma_f32_16x16x32_bf16 v[64:67], v[160:163], v[244:247], v[64:67]
	v_exp_f32_e32 v233, v233
	v_add_f32_e32 v154, v154, v232
	v_mfma_f32_16x16x32_bf16 v[60:63], v[164:167], v[244:247], v[60:63]
	v_exp_f32_e32 v234, v234
	v_add_f32_e32 v154, v154, v233
	v_cvt_pk_bf16_f32 v228, v228, v229
	v_mfma_f32_16x16x32_bf16 v[56:59], v[168:171], v[244:247], v[56:59]
	v_exp_f32_e32 v235, v235
	v_add_f32_e32 v154, v154, v234
	v_cvt_pk_bf16_f32 v229, v230, v231
	v_mfma_f32_16x16x32_bf16 v[52:55], v[172:175], v[244:247], v[52:55]
	v_cvt_pk_bf16_f32 v230, v232, v233
	v_cvt_pk_bf16_f32 v231, v234, v235
	v_add_f32_e32 v154, v154, v235
	v_add_f32_e32 v124, v124, v154
	v_mfma_f32_16x16x32_bf16 v[80:83], v[160:163], v[228:231], v[80:83]
	v_exp_f32_e32 v236, v236
	v_exp_f32_e32 v237, v237
	v_exp_f32_e32 v238, v238
	v_add_f32_e32 v154, v236, v237
	v_mfma_f32_16x16x32_bf16 v[76:79], v[164:167], v[228:231], v[76:79]
	v_exp_f32_e32 v239, v239
	v_add_f32_e32 v154, v154, v238
	v_exp_f32_e32 v104, v104
	v_add_f32_e32 v154, v154, v239
	v_mfma_f32_16x16x32_bf16 v[72:75], v[168:171], v[228:231], v[72:75]
	v_exp_f32_e32 v105, v105
	v_add_f32_e32 v154, v154, v104
	v_exp_f32_e32 v106, v106
	v_add_f32_e32 v154, v154, v105
	v_cvt_pk_bf16_f32 v236, v236, v237
	v_mfma_f32_16x16x32_bf16 v[68:71], v[172:175], v[228:231], v[68:71]
	v_exp_f32_e32 v107, v107
	v_add_f32_e32 v154, v154, v106
	v_cvt_pk_bf16_f32 v237, v238, v239
	v_cvt_pk_bf16_f32 v238, v104, v105
	v_cvt_pk_bf16_f32 v239, v106, v107
	v_add_f32_e32 v154, v154, v107
	v_add_f32_e32 v125, v125, v154
	v_mfma_f32_16x16x32_bf16 v[84:87], v[160:163], v[236:239], v[84:87]
	v_mfma_f32_16x16x32_bf16 v[92:95], v[164:167], v[236:239], v[92:95]
	v_mfma_f32_16x16x32_bf16 v[88:91], v[168:171], v[236:239], v[88:91]
	v_mfma_f32_16x16x32_bf16 v[96:99], v[172:175], v[236:239], v[96:99]
	s_add_i32 vcc_lo, vcc_lo, 0x8000
	s_add_u32 s94, s94, 64
	s_addc_u32 s95, s95, 0
	s_add_i32 s96, s96, 1
	s_waitcnt vmcnt(8)
	s_barrier
	s_cmp_lt_i32 s96, s93
	s_cselect_b32 s7, s95, 0
	s_cselect_b32 s6, s94, s82
	s_lshl_b64 s[6:7], s[6:7], 11
	s_add_u32 s76, s67, s6
	s_addc_u32 s77, s4, s7
	s_add_u32 s6, s5, s6
	s_addc_u32 s7, s58, s7
	s_add_i32 s59, s69, vcc_lo
	s_mov_b32 vcc_hi, m0
	s_mov_b32 m0, s59
	s_nop 0
	global_load_lds_dwordx4 v221, s[76:77]
	s_mov_b32 m0, vcc_hi
	s_add_i32 s66, s59, 0x4000
	s_mov_b32 vcc_hi, m0
	s_mov_b32 m0, s66
	s_nop 0
	global_load_lds_dwordx4 v222, s[6:7]
	s_mov_b32 m0, vcc_hi
	s_add_i32 s66, s59, 0x2000
	s_mov_b32 vcc_hi, m0
	s_mov_b32 m0, s66
	s_nop 0
	global_load_lds_dwordx4 v223, s[76:77]
	s_mov_b32 m0, vcc_hi
	s_addk_i32 s59, 0x6000
	s_mov_b32 s66, m0
	s_mov_b32 m0, s59
	s_nop 0
	global_load_lds_dwordx4 v224, s[6:7]
	s_mov_b32 m0, s66
	s_add_i32 s76, s65, vcc_lo
	s_add_i32 s76, s76, 0x8000
	v_add_u32_e32 v144, s76, v111
	v_add3_u32 v193, s76, v210, v205
	v_add_u32_e32 v145, v144, v204
	v_add_u32_e32 v144, v144, v203
	ds_read_b128 v[160:163], v144
	ds_read_b128 v[164:167], v145
	ds_read_b128 v[168:171], v144 offset:2048
	ds_read_b128 v[172:175], v145 offset:2048
	ds_read_b128 v[128:131], v144 offset:4096
	ds_read_b128 v[132:135], v145 offset:4096
	ds_read_b128 v[136:139], v144 offset:6144
	ds_read_b128 v[140:143], v145 offset:6144
	v_add_u32_e32 v158, v193, v206
	v_add_u32_e32 v159, v193, v207
	v_add_u32_e32 v192, v193, v208
	v_add_u32_e32 v193, v193, v209
	s_waitcnt lgkmcnt(4)
; #define LAS __attribute__((address_space(3)))
; __device__ __forceinline__ s16x4 vtr(const LAS unsigned char* p) { return __builtin_bit_cast(s16x4, __builtin_amdgcn_ds_read_tr16_b64_v4i16((LAS v4i16_t*)p)); }
; __device__ __forceinline__ bf16x8 cat8(s16x4 a, s16x4 b) { return (bf16x8){a[0], a[1], a[2], a[3], b[0], b[1], b[2], b[3]}; }
; __device__ __forceinline__ bf16x8 pack8(const f32x4& a, const f32x4& b) { u32x4 w; w.x = pkbf(a[0], a[1]); w.y = pkbf(a[2], a[3]); w.z = pkbf(b[0], b[1]); w.w = pkbf(b[2], b[3]); return __builtin_bit_cast(bf16x8, w); }
;     ...
;     for (int gh = 0; gh < 4 / GPB; ++gh) {
;         f32x4 S[GPB][4];
; #pragma unroll
;         for (int kb = 0; kb < 4; ++kb) {
;             const bf16x8 kf0 = *(const LAS bf16x8*)(kb0 + (16 * kb) * 128 + kx0), kf1 = *(const LAS bf16x8*)(kb0 + (16 * kb) * 128 + kx1);
; #pragma unroll
;             for (int gi = 0; gi < GPB; ++gi) { S[gi][kb] = __builtin_amdgcn_mfma_f32_16x16x32_bf16(kf0, qf[GPB * gh + gi][0], cinit, 0, 0, 0);
;                 S[gi][kb] = __builtin_amdgcn_mfma_f32_16x16x32_bf16(kf1, qf[GPB * gh + gi][1], S[gi][kb], 0, 0, 0); } }
;         bf16x8 pf[GPB][2];
; #pragma unroll
;         for (int gi = 0; gi < GPB; ++gi) {
;             if (MASK) {
; #pragma unroll
;                 for (int kb = 0; kb < 4; ++kb)
; #pragma unroll
;                     for (int i = 0; i < 4; ++i) { const int rel = rel0 + 16 * kb + 4 * g + i; S[gi][kb][i] = ((unsigned)(rel + 128) > 256u) ? NEGBIG : S[gi][kb][i]; }
;             }
;             ls[GPB * gh + gi] += exp_step<4>(S[gi]);
;             pf[gi][0] = pack8(S[gi][0], S[gi][1]); pf[gi][1] = pack8(S[gi][2], S[gi][3]);
;         }
; #pragma unroll
;         for (int kc = 0; kc < 2; ++kc)
; #pragma unroll
;             for (int db = 0; db < 4; ++db) {
;                 const LAS unsigned char* va = vrow + ((db ^ swz) << 5) + (32 * kc) * 128;
;                 const bf16x8 vf = cat8(vtr(va), vtr(va + 16 * 128));
; #pragma unroll
;                 for (int gi = 0; gi < GPB; ++gi) O[GPB * gh + gi][db] = __builtin_amdgcn_mfma_f32_16x16x32_bf16(vf, pf[gi][kc], O[GPB * gh + gi][db], 0, 0, 0);
;             }
	v_mfma_f32_16x16x32_bf16 v[228:231], v[160:163], v[4:7], v[0:3]
	v_mfma_f32_16x16x32_bf16 v[232:235], v[168:171], v[4:7], v[0:3]
	v_mfma_f32_16x16x32_bf16 v[228:231], v[164:167], v[8:11], v[228:231]
	v_mfma_f32_16x16x32_bf16 v[232:235], v[172:175], v[8:11], v[232:235]
	ds_read_b64_tr_b16 v[176:177], v158 offset:16384
	ds_read_b64_tr_b16 v[178:179], v158 offset:18432
	ds_read_b64_tr_b16 v[180:181], v159 offset:16384
	ds_read_b64_tr_b16 v[182:183], v159 offset:18432
	ds_read_b64_tr_b16 v[184:185], v192 offset:16384
	ds_read_b64_tr_b16 v[186:187], v192 offset:18432
	ds_read_b64_tr_b16 v[188:189], v193 offset:16384
	ds_read_b64_tr_b16 v[190:191], v193 offset:18432
	v_mfma_f32_16x16x32_bf16 v[236:239], v[160:163], v[12:15], v[0:3]
	v_exp_f32_e32 v228, v228
	v_exp_f32_e32 v229, v229
	v_exp_f32_e32 v230, v230
	v_add_f32_e32 v154, v228, v229
	v_mfma_f32_16x16x32_bf16 v[104:107], v[168:171], v[12:15], v[0:3]
	v_exp_f32_e32 v231, v231
	v_add_f32_e32 v154, v154, v230
	v_exp_f32_e32 v232, v232
	v_add_f32_e32 v154, v154, v231
	v_mfma_f32_16x16x32_bf16 v[236:239], v[164:167], v[16:19], v[236:239]
	v_exp_f32_e32 v233, v233
	v_add_f32_e32 v154, v154, v232
	v_exp_f32_e32 v234, v234
	v_add_f32_e32 v154, v154, v233
	v_cvt_pk_bf16_f32 v228, v228, v229
	v_mfma_f32_16x16x32_bf16 v[104:107], v[172:175], v[16:19], v[104:107]
	v_exp_f32_e32 v235, v235
	v_add_f32_e32 v154, v154, v234
	v_cvt_pk_bf16_f32 v229, v230, v231
	v_cvt_pk_bf16_f32 v230, v232, v233
	v_cvt_pk_bf16_f32 v231, v234, v235
	v_add_f32_e32 v154, v154, v235
	v_add_f32_e32 v126, v126, v154
	s_waitcnt lgkmcnt(0)
	v_mfma_f32_16x16x32_bf16 v[244:247], v[160:163], v[20:23], v[0:3]
	v_exp_f32_e32 v236, v236
	v_exp_f32_e32 v237, v237
	v_mfma_f32_16x16x32_bf16 v[248:251], v[168:171], v[20:23], v[0:3]
	v_exp_f32_e32 v238, v238
	v_add_f32_e32 v154, v236, v237
	v_mfma_f32_16x16x32_bf16 v[244:247], v[164:167], v[24:27], v[244:247]
	v_exp_f32_e32 v239, v239
	v_add_f32_e32 v154, v154, v238
	v_mfma_f32_16x16x32_bf16 v[248:251], v[172:175], v[24:27], v[248:251]
	v_exp_f32_e32 v104, v104
	v_add_f32_e32 v154, v154, v239
	v_mfma_f32_16x16x32_bf16 v[48:51], v[176:179], v[228:231], v[48:51]
	v_exp_f32_e32 v105, v105
	v_add_f32_e32 v154, v154, v104
	v_mfma_f32_16x16x32_bf16 v[44:47], v[180:183], v[228:231], v[44:47]
	v_exp_f32_e32 v106, v106
	v_add_f32_e32 v154, v154, v105
	v_cvt_pk_bf16_f32 v236, v236, v237
	v_mfma_f32_16x16x32_bf16 v[40:43], v[184:187], v[228:231], v[40:43]
	v_exp_f32_e32 v107, v107
	v_add_f32_e32 v154, v154, v106
	v_cvt_pk_bf16_f32 v237, v238, v239
	v_mfma_f32_16x16x32_bf16 v[36:39], v[188:191], v[228:231], v[36:39]
	v_cvt_pk_bf16_f32 v238, v104, v105
	v_cvt_pk_bf16_f32 v239, v106, v107
	v_add_f32_e32 v154, v154, v107
	v_add_f32_e32 v127, v127, v154
	v_mfma_f32_16x16x32_bf16 v[228:231], v[160:163], v[28:31], v[0:3]
	v_exp_f32_e32 v244, v244
	v_exp_f32_e32 v245, v245
	v_mfma_f32_16x16x32_bf16 v[232:235], v[168:171], v[28:31], v[0:3]
	v_exp_f32_e32 v246, v246
	v_add_f32_e32 v154, v244, v245
	v_mfma_f32_16x16x32_bf16 v[228:231], v[164:167], v[32:35], v[228:231]
	v_exp_f32_e32 v247, v247
	v_add_f32_e32 v154, v154, v246
	v_mfma_f32_16x16x32_bf16 v[232:235], v[172:175], v[32:35], v[232:235]
	v_exp_f32_e32 v248, v248
	v_add_f32_e32 v154, v154, v247
	v_mfma_f32_16x16x32_bf16 v[64:67], v[176:179], v[236:239], v[64:67]
	v_exp_f32_e32 v249, v249
	v_add_f32_e32 v154, v154, v248
	v_mfma_f32_16x16x32_bf16 v[60:63], v[180:183], v[236:239], v[60:63]
	v_exp_f32_e32 v250, v250
	v_add_f32_e32 v154, v154, v249
	v_cvt_pk_bf16_f32 v244, v244, v245
	v_mfma_f32_16x16x32_bf16 v[56:59], v[184:187], v[236:239], v[56:59]
	v_exp_f32_e32 v251, v251
	v_add_f32_e32 v154, v154, v250
	v_cvt_pk_bf16_f32 v245, v246, v247
	v_mfma_f32_16x16x32_bf16 v[52:55], v[188:191], v[236:239], v[52:55]
	v_cvt_pk_bf16_f32 v246, v248, v249
	v_cvt_pk_bf16_f32 v247, v250, v251
	v_add_f32_e32 v154, v154, v251
	v_add_f32_e32 v124, v124, v154
	ds_read_b64_tr_b16 v[160:161], v158 offset:20480
	ds_read_b64_tr_b16 v[162:163], v158 offset:22528
	ds_read_b64_tr_b16 v[164:165], v159 offset:20480
	ds_read_b64_tr_b16 v[166:167], v159 offset:22528
	ds_read_b64_tr_b16 v[168:169], v192 offset:20480
	ds_read_b64_tr_b16 v[170:171], v192 offset:22528
	ds_read_b64_tr_b16 v[172:173], v193 offset:20480
	ds_read_b64_tr_b16 v[174:175], v193 offset:22528
	v_mfma_f32_16x16x32_bf16 v[236:239], v[128:131], v[4:7], v[0:3]
	v_exp_f32_e32 v228, v228
	v_exp_f32_e32 v229, v229
	v_mfma_f32_16x16x32_bf16 v[104:107], v[136:139], v[4:7], v[0:3]
	v_exp_f32_e32 v230, v230
	v_add_f32_e32 v154, v228, v229
	v_mfma_f32_16x16x32_bf16 v[236:239], v[132:135], v[8:11], v[236:239]
	v_exp_f32_e32 v231, v231
	v_add_f32_e32 v154, v154, v230
	v_mfma_f32_16x16x32_bf16 v[104:107], v[140:143], v[8:11], v[104:107]
	v_exp_f32_e32 v232, v232
	v_add_f32_e32 v154, v154, v231
	v_mfma_f32_16x16x32_bf16 v[80:83], v[176:179], v[244:247], v[80:83]
	v_exp_f32_e32 v233, v233
	v_add_f32_e32 v154, v154, v232
	v_mfma_f32_16x16x32_bf16 v[76:79], v[180:183], v[244:247], v[76:79]
	v_exp_f32_e32 v234, v234
	v_add_f32_e32 v154, v154, v233
	v_cvt_pk_bf16_f32 v228, v228, v229
	v_mfma_f32_16x16x32_bf16 v[72:75], v[184:187], v[244:247], v[72:75]
	v_exp_f32_e32 v235, v235
	v_add_f32_e32 v154, v154, v234
	v_cvt_pk_bf16_f32 v229, v230, v231
	v_mfma_f32_16x16x32_bf16 v[68:71], v[188:191], v[244:247], v[68:71]
	v_cvt_pk_bf16_f32 v230, v232, v233
	v_cvt_pk_bf16_f32 v231, v234, v235
	v_add_f32_e32 v154, v154, v235
	v_add_f32_e32 v125, v125, v154
	v_mfma_f32_16x16x32_bf16 v[244:247], v[128:131], v[12:15], v[0:3]
	v_exp_f32_e32 v236, v236
	v_exp_f32_e32 v237, v237
	v_mfma_f32_16x16x32_bf16 v[248:251], v[136:139], v[12:15], v[0:3]
	v_exp_f32_e32 v238, v238
	v_add_f32_e32 v154, v236, v237
	v_mfma_f32_16x16x32_bf16 v[244:247], v[132:135], v[16:19], v[244:247]
	v_exp_f32_e32 v239, v239
	v_add_f32_e32 v154, v154, v238
	v_mfma_f32_16x16x32_bf16 v[248:251], v[140:143], v[16:19], v[248:251]
	v_exp_f32_e32 v104, v104
	v_add_f32_e32 v154, v154, v239
	v_mfma_f32_16x16x32_bf16 v[84:87], v[176:179], v[228:231], v[84:87]
	v_exp_f32_e32 v105, v105
	v_add_f32_e32 v154, v154, v104
	v_mfma_f32_16x16x32_bf16 v[92:95], v[180:183], v[228:231], v[92:95]
	v_exp_f32_e32 v106, v106
	v_add_f32_e32 v154, v154, v105
	v_cvt_pk_bf16_f32 v236, v236, v237
	v_mfma_f32_16x16x32_bf16 v[88:91], v[184:187], v[228:231], v[88:91]
	v_exp_f32_e32 v107, v107
	v_add_f32_e32 v154, v154, v106
	v_cvt_pk_bf16_f32 v237, v238, v239
	v_mfma_f32_16x16x32_bf16 v[96:99], v[188:191], v[228:231], v[96:99]
	v_cvt_pk_bf16_f32 v238, v104, v105
	v_cvt_pk_bf16_f32 v239, v106, v107
	v_add_f32_e32 v154, v154, v107
	v_add_f32_e32 v126, v126, v154
	s_waitcnt lgkmcnt(0)
; #define LAS __attribute__((address_space(3)))
; __device__ __forceinline__ s16x4 vtr(const LAS unsigned char* p) { return __builtin_bit_cast(s16x4, __builtin_amdgcn_ds_read_tr16_b64_v4i16((LAS v4i16_t*)p)); }
; __device__ __forceinline__ bf16x8 cat8(s16x4 a, s16x4 b) { return (bf16x8){a[0], a[1], a[2], a[3], b[0], b[1], b[2], b[3]}; }
; __device__ __forceinline__ bf16x8 pack8(const f32x4& a, const f32x4& b) { u32x4 w; w.x = pkbf(a[0], a[1]); w.y = pkbf(a[2], a[3]); w.z = pkbf(b[0], b[1]); w.w = pkbf(b[2], b[3]); return __builtin_bit_cast(bf16x8, w); }
; template <int NI> __device__ __forceinline__ void ring_wait() { asm volatile("s_waitcnt vmcnt(%0)" :: "n"(2 * NI) : "memory"); __syncthreads(); }
;     ...
;             pf[gi][0] = pack8(S[gi][0], S[gi][1]); pf[gi][1] = pack8(S[gi][2], S[gi][3]);
;         }
; #pragma unroll
;         for (int kc = 0; kc < 2; ++kc)
; #pragma unroll
;             for (int db = 0; db < 4; ++db) {
;                 const LAS unsigned char* va = vrow + ((db ^ swz) << 5) + (32 * kc) * 128;
;                 const bf16x8 vf = cat8(vtr(va), vtr(va + 16 * 128));
; #pragma unroll
;                 for (int gi = 0; gi < GPB; ++gi) O[GPB * gh + gi][db] = __builtin_amdgcn_mfma_f32_16x16x32_bf16(vf, pf[gi][kc], O[GPB * gh + gi][db], 0, 0, 0);
;             }
; __device__ __forceinline__ void na_phase(LAS unsigned char* lds, const bf16_t* Q, const bf16_t* K, const bf16_t* V, bf16_t* Ob, const float* rpb, float negb) {
;     ...
;         for (int t = 0; t < 4; ++t) {
;             dma_tile<2>(lds + ((t + 3) & 3) * NA_BUF, K, V, NA_ROW0(t + 3), DM, dl, w);
;             const LAS unsigned char* buf = lds + (t & 3) * NA_BUF;
;             full_tile<0, 1, 2>(O, ls, qf, negb, buf + hh * 8192, buf + 2 * 8192 + hh * 8192, lane, 0);
;             ring_wait<4>();
;         }
	v_mfma_f32_16x16x32_bf16 v[228:231], v[128:131], v[20:23], v[0:3]
	v_exp_f32_e32 v244, v244
	v_exp_f32_e32 v245, v245
	v_mfma_f32_16x16x32_bf16 v[232:235], v[136:139], v[20:23], v[0:3]
	v_exp_f32_e32 v246, v246
	v_add_f32_e32 v154, v244, v245
	v_mfma_f32_16x16x32_bf16 v[228:231], v[132:135], v[24:27], v[228:231]
	v_exp_f32_e32 v247, v247
	v_add_f32_e32 v154, v154, v246
	v_mfma_f32_16x16x32_bf16 v[232:235], v[140:143], v[24:27], v[232:235]
	v_exp_f32_e32 v248, v248
	v_add_f32_e32 v154, v154, v247
	v_mfma_f32_16x16x32_bf16 v[48:51], v[160:163], v[236:239], v[48:51]
	v_exp_f32_e32 v249, v249
	v_add_f32_e32 v154, v154, v248
	v_mfma_f32_16x16x32_bf16 v[44:47], v[164:167], v[236:239], v[44:47]
	v_exp_f32_e32 v250, v250
	v_add_f32_e32 v154, v154, v249
	v_cvt_pk_bf16_f32 v244, v244, v245
	v_mfma_f32_16x16x32_bf16 v[40:43], v[168:171], v[236:239], v[40:43]
	v_exp_f32_e32 v251, v251
	v_add_f32_e32 v154, v154, v250
	v_cvt_pk_bf16_f32 v245, v246, v247
	v_mfma_f32_16x16x32_bf16 v[36:39], v[172:175], v[236:239], v[36:39]
	v_cvt_pk_bf16_f32 v246, v248, v249
	v_cvt_pk_bf16_f32 v247, v250, v251
	v_add_f32_e32 v154, v154, v251
	v_add_f32_e32 v127, v127, v154
	v_mfma_f32_16x16x32_bf16 v[236:239], v[128:131], v[28:31], v[0:3]
	v_exp_f32_e32 v228, v228
	v_exp_f32_e32 v229, v229
	v_mfma_f32_16x16x32_bf16 v[104:107], v[136:139], v[28:31], v[0:3]
	v_exp_f32_e32 v230, v230
	v_add_f32_e32 v154, v228, v229
	v_mfma_f32_16x16x32_bf16 v[236:239], v[132:135], v[32:35], v[236:239]
	v_exp_f32_e32 v231, v231
	v_add_f32_e32 v154, v154, v230
	v_mfma_f32_16x16x32_bf16 v[104:107], v[140:143], v[32:35], v[104:107]
	v_exp_f32_e32 v232, v232
	v_add_f32_e32 v154, v154, v231
	v_mfma_f32_16x16x32_bf16 v[64:67], v[160:163], v[244:247], v[64:67]
	v_exp_f32_e32 v233, v233
	v_add_f32_e32 v154, v154, v232
	v_mfma_f32_16x16x32_bf16 v[60:63], v[164:167], v[244:247], v[60:63]
	v_exp_f32_e32 v234, v234
	v_add_f32_e32 v154, v154, v233
	v_cvt_pk_bf16_f32 v228, v228, v229
	v_mfma_f32_16x16x32_bf16 v[56:59], v[168:171], v[244:247], v[56:59]
	v_exp_f32_e32 v235, v235
	v_add_f32_e32 v154, v154, v234
	v_cvt_pk_bf16_f32 v229, v230, v231
	v_mfma_f32_16x16x32_bf16 v[52:55], v[172:175], v[244:247], v[52:55]
	v_cvt_pk_bf16_f32 v230, v232, v233
	v_cvt_pk_bf16_f32 v231, v234, v235
	v_add_f32_e32 v154, v154, v235
	v_add_f32_e32 v124, v124, v154
	v_mfma_f32_16x16x32_bf16 v[80:83], v[160:163], v[228:231], v[80:83]
	v_exp_f32_e32 v236, v236
	v_exp_f32_e32 v237, v237
	v_exp_f32_e32 v238, v238
	v_add_f32_e32 v154, v236, v237
	v_mfma_f32_16x16x32_bf16 v[76:79], v[164:167], v[228:231], v[76:79]
	v_exp_f32_e32 v239, v239
	v_add_f32_e32 v154, v154, v238
	v_exp_f32_e32 v104, v104
	v_add_f32_e32 v154, v154, v239
	v_mfma_f32_16x16x32_bf16 v[72:75], v[168:171], v[228:231], v[72:75]
	v_exp_f32_e32 v105, v105
	v_add_f32_e32 v154, v154, v104
	v_exp_f32_e32 v106, v106
	v_add_f32_e32 v154, v154, v105
	v_cvt_pk_bf16_f32 v236, v236, v237
	v_mfma_f32_16x16x32_bf16 v[68:71], v[172:175], v[228:231], v[68:71]
	v_exp_f32_e32 v107, v107
	v_add_f32_e32 v154, v154, v106
	v_cvt_pk_bf16_f32 v237, v238, v239
	v_cvt_pk_bf16_f32 v238, v104, v105
	v_cvt_pk_bf16_f32 v239, v106, v107
	v_add_f32_e32 v154, v154, v107
	v_add_f32_e32 v125, v125, v154
	v_mfma_f32_16x16x32_bf16 v[84:87], v[160:163], v[236:239], v[84:87]
	v_mfma_f32_16x16x32_bf16 v[92:95], v[164:167], v[236:239], v[92:95]
	v_mfma_f32_16x16x32_bf16 v[88:91], v[168:171], v[236:239], v[88:91]
	v_mfma_f32_16x16x32_bf16 v[96:99], v[172:175], v[236:239], v[96:99]
	s_add_i32 vcc_lo, vcc_lo, 0x8000
	s_add_u32 s94, s94, 64
	s_addc_u32 s95, s95, 0
	s_add_i32 s96, s96, 1
	s_waitcnt vmcnt(8)
	s_barrier
	s_cmp_lt_i32 s96, s93
	s_cselect_b32 s7, s95, 0
	s_cselect_b32 s6, s94, s82
	s_lshl_b64 s[6:7], s[6:7], 11
	s_add_u32 s76, s67, s6
	s_addc_u32 s77, s4, s7
	s_add_u32 s6, s5, s6
	s_addc_u32 s7, s58, s7
	s_add_i32 s59, s69, vcc_lo
	s_mov_b32 vcc_hi, m0
	s_mov_b32 m0, s59
	s_nop 0
	global_load_lds_dwordx4 v221, s[76:77]
	s_mov_b32 m0, vcc_hi
	s_add_i32 s66, s59, 0x4000
	s_mov_b32 vcc_hi, m0
	s_mov_b32 m0, s66
	s_nop 0
	global_load_lds_dwordx4 v222, s[6:7]
	s_mov_b32 m0, vcc_hi
	s_add_i32 s66, s59, 0x2000
	s_mov_b32 vcc_hi, m0
	s_mov_b32 m0, s66
	s_nop 0
	global_load_lds_dwordx4 v223, s[76:77]
	s_mov_b32 m0, vcc_hi
	s_addk_i32 s59, 0x6000
	s_mov_b32 s66, m0
	s_mov_b32 m0, s59
	s_nop 0
	global_load_lds_dwordx4 v224, s[6:7]
	s_mov_b32 m0, s66
	s_add_i32 s76, s65, vcc_lo
	s_add_i32 s76, s76, 0x8000
	v_add_u32_e32 v144, s76, v111
	v_add3_u32 v193, s76, v210, v205
	v_add_u32_e32 v145, v144, v204
	v_add_u32_e32 v144, v144, v203
	ds_read_b128 v[160:163], v144
	ds_read_b128 v[164:167], v145
	ds_read_b128 v[168:171], v144 offset:2048
	ds_read_b128 v[172:175], v145 offset:2048
	ds_read_b128 v[128:131], v144 offset:4096
	ds_read_b128 v[132:135], v145 offset:4096
	ds_read_b128 v[136:139], v144 offset:6144
	ds_read_b128 v[140:143], v145 offset:6144
	v_add_u32_e32 v158, v193, v206
	v_add_u32_e32 v159, v193, v207
	v_add_u32_e32 v192, v193, v208
	v_add_u32_e32 v193, v193, v209
	s_waitcnt lgkmcnt(4)
; #define LAS __attribute__((address_space(3)))
; __device__ __forceinline__ s16x4 vtr(const LAS unsigned char* p) { return __builtin_bit_cast(s16x4, __builtin_amdgcn_ds_read_tr16_b64_v4i16((LAS v4i16_t*)p)); }
; __device__ __forceinline__ bf16x8 cat8(s16x4 a, s16x4 b) { return (bf16x8){a[0], a[1], a[2], a[3], b[0], b[1], b[2], b[3]}; }
; __device__ __forceinline__ bf16x8 pack8(const f32x4& a, const f32x4& b) { u32x4 w; w.x = pkbf(a[0], a[1]); w.y = pkbf(a[2], a[3]); w.z = pkbf(b[0], b[1]); w.w = pkbf(b[2], b[3]); return __builtin_bit_cast(bf16x8, w); }
;     ...
;     for (int gh = 0; gh < 4 / GPB; ++gh) {
;         f32x4 S[GPB][4];
; #pragma unroll
;         for (int kb = 0; kb < 4; ++kb) {
;             const bf16x8 kf0 = *(const LAS bf16x8*)(kb0 + (16 * kb) * 128 + kx0), kf1 = *(const LAS bf16x8*)(kb0 + (16 * kb) * 128 + kx1);
; #pragma unroll
;             for (int gi = 0; gi < GPB; ++gi) { S[gi][kb] = __builtin_amdgcn_mfma_f32_16x16x32_bf16(kf0, qf[GPB * gh + gi][0], cinit, 0, 0, 0);
;                 S[gi][kb] = __builtin_amdgcn_mfma_f32_16x16x32_bf16(kf1, qf[GPB * gh + gi][1], S[gi][kb], 0, 0, 0); } }
;         bf16x8 pf[GPB][2];
; #pragma unroll
;         for (int gi = 0; gi < GPB; ++gi) {
;             if (MASK) {
; #pragma unroll
;                 for (int kb = 0; kb < 4; ++kb)
; #pragma unroll
;                     for (int i = 0; i < 4; ++i) { const int rel = rel0 + 16 * kb + 4 * g + i; S[gi][kb][i] = ((unsigned)(rel + 128) > 256u) ? NEGBIG : S[gi][kb][i]; }
;             }
;             ls[GPB * gh + gi] += exp_step<4>(S[gi]);
;             pf[gi][0] = pack8(S[gi][0], S[gi][1]); pf[gi][1] = pack8(S[gi][2], S[gi][3]);
;         }
; #pragma unroll
;         for (int kc = 0; kc < 2; ++kc)
; #pragma unroll
;             for (int db = 0; db < 4; ++db) {
;                 const LAS unsigned char* va = vrow + ((db ^ swz) << 5) + (32 * kc) * 128;
;                 const bf16x8 vf = cat8(vtr(va), vtr(va + 16 * 128));
; #pragma unroll
;                 for (int gi = 0; gi < GPB; ++gi) O[GPB * gh + gi][db] = __builtin_amdgcn_mfma_f32_16x16x32_bf16(vf, pf[gi][kc], O[GPB * gh + gi][db], 0, 0, 0);
;             }
	v_mfma_f32_16x16x32_bf16 v[228:231], v[160:163], v[4:7], v[0:3]
	v_mfma_f32_16x16x32_bf16 v[232:235], v[168:171], v[4:7], v[0:3]
	v_mfma_f32_16x16x32_bf16 v[228:231], v[164:167], v[8:11], v[228:231]
	v_mfma_f32_16x16x32_bf16 v[232:235], v[172:175], v[8:11], v[232:235]
	ds_read_b64_tr_b16 v[176:177], v158 offset:16384
	ds_read_b64_tr_b16 v[178:179], v158 offset:18432
	ds_read_b64_tr_b16 v[180:181], v159 offset:16384
	ds_read_b64_tr_b16 v[182:183], v159 offset:18432
	ds_read_b64_tr_b16 v[184:185], v192 offset:16384
	ds_read_b64_tr_b16 v[186:187], v192 offset:18432
	ds_read_b64_tr_b16 v[188:189], v193 offset:16384
	ds_read_b64_tr_b16 v[190:191], v193 offset:18432
	v_mfma_f32_16x16x32_bf16 v[236:239], v[160:163], v[12:15], v[0:3]
	v_exp_f32_e32 v228, v228
	v_exp_f32_e32 v229, v229
	v_exp_f32_e32 v230, v230
	v_add_f32_e32 v154, v228, v229
	v_mfma_f32_16x16x32_bf16 v[104:107], v[168:171], v[12:15], v[0:3]
	v_exp_f32_e32 v231, v231
	v_add_f32_e32 v154, v154, v230
	v_exp_f32_e32 v232, v232
	v_add_f32_e32 v154, v154, v231
	v_mfma_f32_16x16x32_bf16 v[236:239], v[164:167], v[16:19], v[236:239]
	v_exp_f32_e32 v233, v233
	v_add_f32_e32 v154, v154, v232
	v_exp_f32_e32 v234, v234
	v_add_f32_e32 v154, v154, v233
	v_cvt_pk_bf16_f32 v228, v228, v229
	v_mfma_f32_16x16x32_bf16 v[104:107], v[172:175], v[16:19], v[104:107]
	v_exp_f32_e32 v235, v235
	v_add_f32_e32 v154, v154, v234
	v_cvt_pk_bf16_f32 v229, v230, v231
	v_cvt_pk_bf16_f32 v230, v232, v233
	v_cvt_pk_bf16_f32 v231, v234, v235
	v_add_f32_e32 v154, v154, v235
	v_add_f32_e32 v126, v126, v154
	s_waitcnt lgkmcnt(0)
	v_mfma_f32_16x16x32_bf16 v[244:247], v[160:163], v[20:23], v[0:3]
	v_exp_f32_e32 v236, v236
	v_exp_f32_e32 v237, v237
	v_mfma_f32_16x16x32_bf16 v[248:251], v[168:171], v[20:23], v[0:3]
	v_exp_f32_e32 v238, v238
	v_add_f32_e32 v154, v236, v237
	v_mfma_f32_16x16x32_bf16 v[244:247], v[164:167], v[24:27], v[244:247]
	v_exp_f32_e32 v239, v239
	v_add_f32_e32 v154, v154, v238
	v_mfma_f32_16x16x32_bf16 v[248:251], v[172:175], v[24:27], v[248:251]
	v_exp_f32_e32 v104, v104
	v_add_f32_e32 v154, v154, v239
	v_mfma_f32_16x16x32_bf16 v[48:51], v[176:179], v[228:231], v[48:51]
	v_exp_f32_e32 v105, v105
	v_add_f32_e32 v154, v154, v104
	v_mfma_f32_16x16x32_bf16 v[44:47], v[180:183], v[228:231], v[44:47]
	v_exp_f32_e32 v106, v106
	v_add_f32_e32 v154, v154, v105
	v_cvt_pk_bf16_f32 v236, v236, v237
	v_mfma_f32_16x16x32_bf16 v[40:43], v[184:187], v[228:231], v[40:43]
	v_exp_f32_e32 v107, v107
	v_add_f32_e32 v154, v154, v106
	v_cvt_pk_bf16_f32 v237, v238, v239
	v_mfma_f32_16x16x32_bf16 v[36:39], v[188:191], v[228:231], v[36:39]
	v_cvt_pk_bf16_f32 v238, v104, v105
	v_cvt_pk_bf16_f32 v239, v106, v107
	v_add_f32_e32 v154, v154, v107
	v_add_f32_e32 v127, v127, v154
	v_mfma_f32_16x16x32_bf16 v[228:231], v[160:163], v[28:31], v[0:3]
	v_exp_f32_e32 v244, v244
	v_exp_f32_e32 v245, v245
	v_mfma_f32_16x16x32_bf16 v[232:235], v[168:171], v[28:31], v[0:3]
	v_exp_f32_e32 v246, v246
	v_add_f32_e32 v154, v244, v245
	v_mfma_f32_16x16x32_bf16 v[228:231], v[164:167], v[32:35], v[228:231]
	v_exp_f32_e32 v247, v247
	v_add_f32_e32 v154, v154, v246
	v_mfma_f32_16x16x32_bf16 v[232:235], v[172:175], v[32:35], v[232:235]
	v_exp_f32_e32 v248, v248
	v_add_f32_e32 v154, v154, v247
	v_mfma_f32_16x16x32_bf16 v[64:67], v[176:179], v[236:239], v[64:67]
	v_exp_f32_e32 v249, v249
	v_add_f32_e32 v154, v154, v248
	v_mfma_f32_16x16x32_bf16 v[60:63], v[180:183], v[236:239], v[60:63]
	v_exp_f32_e32 v250, v250
	v_add_f32_e32 v154, v154, v249
	v_cvt_pk_bf16_f32 v244, v244, v245
	v_mfma_f32_16x16x32_bf16 v[56:59], v[184:187], v[236:239], v[56:59]
	v_exp_f32_e32 v251, v251
	v_add_f32_e32 v154, v154, v250
	v_cvt_pk_bf16_f32 v245, v246, v247
	v_mfma_f32_16x16x32_bf16 v[52:55], v[188:191], v[236:239], v[52:55]
	v_cvt_pk_bf16_f32 v246, v248, v249
	v_cvt_pk_bf16_f32 v247, v250, v251
	v_add_f32_e32 v154, v154, v251
	v_add_f32_e32 v124, v124, v154
	ds_read_b64_tr_b16 v[160:161], v158 offset:20480
	ds_read_b64_tr_b16 v[162:163], v158 offset:22528
	ds_read_b64_tr_b16 v[164:165], v159 offset:20480
	ds_read_b64_tr_b16 v[166:167], v159 offset:22528
	ds_read_b64_tr_b16 v[168:169], v192 offset:20480
	ds_read_b64_tr_b16 v[170:171], v192 offset:22528
	ds_read_b64_tr_b16 v[172:173], v193 offset:20480
	ds_read_b64_tr_b16 v[174:175], v193 offset:22528
	v_mfma_f32_16x16x32_bf16 v[236:239], v[128:131], v[4:7], v[0:3]
	v_exp_f32_e32 v228, v228
	v_exp_f32_e32 v229, v229
	v_mfma_f32_16x16x32_bf16 v[104:107], v[136:139], v[4:7], v[0:3]
	v_exp_f32_e32 v230, v230
	v_add_f32_e32 v154, v228, v229
	v_mfma_f32_16x16x32_bf16 v[236:239], v[132:135], v[8:11], v[236:239]
	v_exp_f32_e32 v231, v231
	v_add_f32_e32 v154, v154, v230
	v_mfma_f32_16x16x32_bf16 v[104:107], v[140:143], v[8:11], v[104:107]
	v_exp_f32_e32 v232, v232
	v_add_f32_e32 v154, v154, v231
	v_mfma_f32_16x16x32_bf16 v[80:83], v[176:179], v[244:247], v[80:83]
	v_exp_f32_e32 v233, v233
	v_add_f32_e32 v154, v154, v232
	v_mfma_f32_16x16x32_bf16 v[76:79], v[180:183], v[244:247], v[76:79]
	v_exp_f32_e32 v234, v234
	v_add_f32_e32 v154, v154, v233
	v_cvt_pk_bf16_f32 v228, v228, v229
	v_mfma_f32_16x16x32_bf16 v[72:75], v[184:187], v[244:247], v[72:75]
	v_exp_f32_e32 v235, v235
	v_add_f32_e32 v154, v154, v234
	v_cvt_pk_bf16_f32 v229, v230, v231
	v_mfma_f32_16x16x32_bf16 v[68:71], v[188:191], v[244:247], v[68:71]
	v_cvt_pk_bf16_f32 v230, v232, v233
	v_cvt_pk_bf16_f32 v231, v234, v235
	v_add_f32_e32 v154, v154, v235
	v_add_f32_e32 v125, v125, v154
	v_mfma_f32_16x16x32_bf16 v[244:247], v[128:131], v[12:15], v[0:3]
	v_exp_f32_e32 v236, v236
	v_exp_f32_e32 v237, v237
	v_mfma_f32_16x16x32_bf16 v[248:251], v[136:139], v[12:15], v[0:3]
	v_exp_f32_e32 v238, v238
	v_add_f32_e32 v154, v236, v237
	v_mfma_f32_16x16x32_bf16 v[244:247], v[132:135], v[16:19], v[244:247]
	v_exp_f32_e32 v239, v239
	v_add_f32_e32 v154, v154, v238
	v_mfma_f32_16x16x32_bf16 v[248:251], v[140:143], v[16:19], v[248:251]
	v_exp_f32_e32 v104, v104
	v_add_f32_e32 v154, v154, v239
	v_mfma_f32_16x16x32_bf16 v[84:87], v[176:179], v[228:231], v[84:87]
	v_exp_f32_e32 v105, v105
	v_add_f32_e32 v154, v154, v104
	v_mfma_f32_16x16x32_bf16 v[92:95], v[180:183], v[228:231], v[92:95]
	v_exp_f32_e32 v106, v106
	v_add_f32_e32 v154, v154, v105
	v_cvt_pk_bf16_f32 v236, v236, v237
	v_mfma_f32_16x16x32_bf16 v[88:91], v[184:187], v[228:231], v[88:91]
	v_exp_f32_e32 v107, v107
	v_add_f32_e32 v154, v154, v106
	v_cvt_pk_bf16_f32 v237, v238, v239
	v_mfma_f32_16x16x32_bf16 v[96:99], v[188:191], v[228:231], v[96:99]
	v_cvt_pk_bf16_f32 v238, v104, v105
	v_cvt_pk_bf16_f32 v239, v106, v107
	v_add_f32_e32 v154, v154, v107
	v_add_f32_e32 v126, v126, v154
	s_waitcnt lgkmcnt(0)
; #define LAS __attribute__((address_space(3)))
; __device__ __forceinline__ s16x4 vtr(const LAS unsigned char* p) { return __builtin_bit_cast(s16x4, __builtin_amdgcn_ds_read_tr16_b64_v4i16((LAS v4i16_t*)p)); }
; __device__ __forceinline__ bf16x8 cat8(s16x4 a, s16x4 b) { return (bf16x8){a[0], a[1], a[2], a[3], b[0], b[1], b[2], b[3]}; }
; __device__ __forceinline__ bf16x8 pack8(const f32x4& a, const f32x4& b) { u32x4 w; w.x = pkbf(a[0], a[1]); w.y = pkbf(a[2], a[3]); w.z = pkbf(b[0], b[1]); w.w = pkbf(b[2], b[3]); return __builtin_bit_cast(bf16x8, w); }
; template <int NI> __device__ __forceinline__ void ring_wait() { asm volatile("s_waitcnt vmcnt(%0)" :: "n"(2 * NI) : "memory"); __syncthreads(); }
;     ...
;             pf[gi][0] = pack8(S[gi][0], S[gi][1]); pf[gi][1] = pack8(S[gi][2], S[gi][3]);
;         }
; #pragma unroll
;         for (int kc = 0; kc < 2; ++kc)
; #pragma unroll
;             for (int db = 0; db < 4; ++db) {
;                 const LAS unsigned char* va = vrow + ((db ^ swz) << 5) + (32 * kc) * 128;
;                 const bf16x8 vf = cat8(vtr(va), vtr(va + 16 * 128));
; #pragma unroll
;                 for (int gi = 0; gi < GPB; ++gi) O[GPB * gh + gi][db] = __builtin_amdgcn_mfma_f32_16x16x32_bf16(vf, pf[gi][kc], O[GPB * gh + gi][db], 0, 0, 0);
;             }
; __device__ __forceinline__ void na_phase(LAS unsigned char* lds, const bf16_t* Q, const bf16_t* K, const bf16_t* V, bf16_t* Ob, const float* rpb, float negb) {
;     ...
;             ring_wait<4>();
;         }
;         for (int t = 4; t < NT; ++t) {
;             dma_tile<2>(lds + ((t + 3) & 3) * NA_BUF, K, V, NA_ROW0(t + 3), DM, dl, w);
;             const LAS unsigned char* buf = lds + (t & 3) * NA_BUF;
;             const int kr = kr_lo + t - 4; const bool rv = kr >= r0w && kr < r0w + 8;
;             if (rv) na_local_tile(O, ls, qf, negb, buf + hh * 8192, buf + 2 * 8192 + hh * 8192, lane, tab + hh * 512 + (kr - r + 7) * 31, true);
	v_mfma_f32_16x16x32_bf16 v[228:231], v[128:131], v[20:23], v[0:3]
	v_exp_f32_e32 v244, v244
	v_exp_f32_e32 v245, v245
	v_mfma_f32_16x16x32_bf16 v[232:235], v[136:139], v[20:23], v[0:3]
	v_exp_f32_e32 v246, v246
	v_add_f32_e32 v154, v244, v245
	v_mfma_f32_16x16x32_bf16 v[228:231], v[132:135], v[24:27], v[228:231]
	v_exp_f32_e32 v247, v247
	v_add_f32_e32 v154, v154, v246
	v_mfma_f32_16x16x32_bf16 v[232:235], v[140:143], v[24:27], v[232:235]
	v_exp_f32_e32 v248, v248
	v_add_f32_e32 v154, v154, v247
	v_mfma_f32_16x16x32_bf16 v[48:51], v[160:163], v[236:239], v[48:51]
	v_exp_f32_e32 v249, v249
	v_add_f32_e32 v154, v154, v248
	v_mfma_f32_16x16x32_bf16 v[44:47], v[164:167], v[236:239], v[44:47]
	v_exp_f32_e32 v250, v250
	v_add_f32_e32 v154, v154, v249
	v_cvt_pk_bf16_f32 v244, v244, v245
	v_mfma_f32_16x16x32_bf16 v[40:43], v[168:171], v[236:239], v[40:43]
	v_exp_f32_e32 v251, v251
	v_add_f32_e32 v154, v154, v250
	v_cvt_pk_bf16_f32 v245, v246, v247
	v_mfma_f32_16x16x32_bf16 v[36:39], v[172:175], v[236:239], v[36:39]
	v_cvt_pk_bf16_f32 v246, v248, v249
	v_cvt_pk_bf16_f32 v247, v250, v251
	v_add_f32_e32 v154, v154, v251
	v_add_f32_e32 v127, v127, v154
	v_mfma_f32_16x16x32_bf16 v[236:239], v[128:131], v[28:31], v[0:3]
	v_exp_f32_e32 v228, v228
	v_exp_f32_e32 v229, v229
	v_mfma_f32_16x16x32_bf16 v[104:107], v[136:139], v[28:31], v[0:3]
	v_exp_f32_e32 v230, v230
	v_add_f32_e32 v154, v228, v229
	v_mfma_f32_16x16x32_bf16 v[236:239], v[132:135], v[32:35], v[236:239]
	v_exp_f32_e32 v231, v231
	v_add_f32_e32 v154, v154, v230
	v_mfma_f32_16x16x32_bf16 v[104:107], v[140:143], v[32:35], v[104:107]
	v_exp_f32_e32 v232, v232
	v_add_f32_e32 v154, v154, v231
	v_mfma_f32_16x16x32_bf16 v[64:67], v[160:163], v[244:247], v[64:67]
	v_exp_f32_e32 v233, v233
	v_add_f32_e32 v154, v154, v232
	v_mfma_f32_16x16x32_bf16 v[60:63], v[164:167], v[244:247], v[60:63]
	v_exp_f32_e32 v234, v234
	v_add_f32_e32 v154, v154, v233
	v_cvt_pk_bf16_f32 v228, v228, v229
	v_mfma_f32_16x16x32_bf16 v[56:59], v[168:171], v[244:247], v[56:59]
	v_exp_f32_e32 v235, v235
	v_add_f32_e32 v154, v154, v234
	v_cvt_pk_bf16_f32 v229, v230, v231
	v_mfma_f32_16x16x32_bf16 v[52:55], v[172:175], v[244:247], v[52:55]
	v_cvt_pk_bf16_f32 v230, v232, v233
	v_cvt_pk_bf16_f32 v231, v234, v235
	v_add_f32_e32 v154, v154, v235
	v_add_f32_e32 v124, v124, v154
	v_mfma_f32_16x16x32_bf16 v[80:83], v[160:163], v[228:231], v[80:83]
	v_exp_f32_e32 v236, v236
	v_exp_f32_e32 v237, v237
	v_exp_f32_e32 v238, v238
	v_add_f32_e32 v154, v236, v237
	v_mfma_f32_16x16x32_bf16 v[76:79], v[164:167], v[228:231], v[76:79]
	v_exp_f32_e32 v239, v239
	v_add_f32_e32 v154, v154, v238
	v_exp_f32_e32 v104, v104
	v_add_f32_e32 v154, v154, v239
	v_mfma_f32_16x16x32_bf16 v[72:75], v[168:171], v[228:231], v[72:75]
	v_exp_f32_e32 v105, v105
	v_add_f32_e32 v154, v154, v104
	v_exp_f32_e32 v106, v106
	v_add_f32_e32 v154, v154, v105
	v_cvt_pk_bf16_f32 v236, v236, v237
	v_mfma_f32_16x16x32_bf16 v[68:71], v[172:175], v[228:231], v[68:71]
	v_exp_f32_e32 v107, v107
	v_add_f32_e32 v154, v154, v106
	v_cvt_pk_bf16_f32 v237, v238, v239
	v_cvt_pk_bf16_f32 v238, v104, v105
	v_cvt_pk_bf16_f32 v239, v106, v107
	v_add_f32_e32 v154, v154, v107
	v_add_f32_e32 v125, v125, v154
	v_mfma_f32_16x16x32_bf16 v[84:87], v[160:163], v[236:239], v[84:87]
	v_mfma_f32_16x16x32_bf16 v[92:95], v[164:167], v[236:239], v[92:95]
	v_mfma_f32_16x16x32_bf16 v[88:91], v[168:171], v[236:239], v[88:91]
	v_mfma_f32_16x16x32_bf16 v[96:99], v[172:175], v[236:239], v[96:99]
	s_add_i32 vcc_lo, vcc_lo, 0x8000
	s_add_u32 s94, s94, 64
	s_addc_u32 s95, s95, 0
	s_add_i32 s96, s96, 1
	s_waitcnt vmcnt(8)
	s_barrier
	s_cmp_lt_i32 s93, 5
	s_cbranch_scc1 .LBB0_361
	s_add_i32 s97, s97, -4
	s_min_u32 s94, s97, 0x78
	s_add_i32 s95, s94, 8
	s_add_i32 s96, s93, -4
	s_cmp_gt_u32 s68, 4
	s_cselect_b32 s7, 0, 0
	s_cselect_b32 s6, s68, 4
	s_lshl_b64 s[6:7], s[6:7], 6
	s_add_u32 s6, s6, s61
	s_addc_u32 s7, s7, 0
	s_add_u32 s59, s6, 0xffffffc0
	s_addc_u32 s66, s7, -1
	s_mov_b32 s7, s68
	s_mul_i32 s6, s60, 0x7c
	s_mulk_i32 s7, 0x7c
	s_sub_i32 s6, s6, s7
	s_mov_b32 s97, 0
	v_add_u32_e32 v128, s6, v219
	s_add_i32 s68, s60, -4
	v_add_u32_e32 v129, s6, v220
	s_mov_b32 s6, 0x20000
	s_branch .LBB0_383

; #define LAS __attribute__((address_space(3)))
; __device__ __forceinline__ void na_local_tile(f32x4 (&O)[4][4], float (&ls)[4], const bf16x8 (&qf)[4][2], float negb,
;                                               const LAS unsigned char* Kt, const LAS unsigned char* Vt, int lane, const LAS float* bias_row, bool rowvalid) {
;     ...
; #pragma unroll
;     for (int grp = 0; grp < 4; ++grp) {
;         const int kwin = grp == 0 ? 0 : (grp == 1 ? 8 : (grp == 2 ? 24 : 32));
;         f32x4 S[2];
; #pragma unroll
;         for (int k2 = 0; k2 < 2; ++k2) {
;             const bf16x8 kf0 = *(const LAS bf16x8*)(kb0 + (kwin + 16 * k2) * 128 + kx0), kf1 = *(const LAS bf16x8*)(kb0 + (kwin + 16 * k2) * 128 + kx1);
;             S[k2] = __builtin_amdgcn_mfma_f32_16x16x32_bf16(kf0, qf[grp][0], (f32x4){negb, negb, negb, negb}, 0, 0, 0);
;             S[k2] = __builtin_amdgcn_mfma_f32_16x16x32_bf16(kf1, qf[grp][1], S[k2], 0, 0, 0); }
;         const int c = 16 * grp + l15; const int c0 = rowvalid ? min(max(c - 8, 0), 48) : 4096;
;         const LAS float* bl = bias_row + (15 - c + 4 * g);
; #pragma unroll
;         for (int k2 = 0; k2 < 2; ++k2)
; #pragma unroll
;             for (int i = 0; i < 4; ++i) { const int kc = kwin + 16 * k2 + 4 * g + i; const float bias = bl[kwin + 16 * k2 + i];
;                 S[k2][i] = ((unsigned)(kc - c0) < 16u) ? S[k2][i] + bias : NEGBIG; }
; __device__ __forceinline__ void na_phase(LAS unsigned char* lds, const bf16_t* Q, const bf16_t* K, const bf16_t* V, bf16_t* Ob, const float* rpb, float negb) {
;     ...
;         for (int t = 4; t < NT; ++t) {
;             dma_tile<2>(lds + ((t + 3) & 3) * NA_BUF, K, V, NA_ROW0(t + 3), DM, dl, w);
;             const LAS unsigned char* buf = lds + (t & 3) * NA_BUF;
;             const int kr = kr_lo + t - 4; const bool rv = kr >= r0w && kr < r0w + 8;
;             if (rv) na_local_tile(O, ls, qf, negb, buf + hh * 8192, buf + 2 * 8192 + hh * 8192, lane, tab + hh * 512 + (kr - r + 7) * 31, true);
.LBB0_383:
	s_add_i32 s60, s6, 0x18000
	s_and_b32 s60, s60, 0x18000
	s_add_i32 s7, s97, 7
	s_add_i32 vcc_lo, s60, 0
	s_cmp_lt_i32 s7, s93
	s_cselect_b32 s61, s66, 0
	s_cselect_b32 s60, s59, s82
	s_lshl_b64 s[60:61], s[60:61], 11
	s_add_u32 s76, s67, s60
	s_addc_u32 s77, s4, s61
	s_add_u32 s60, s5, s60
	s_addc_u32 s61, s58, s61
	s_add_i32 s7, s63, vcc_lo
	s_add_i32 vcc_lo, s7, 0x4000
	s_mov_b32 vcc_hi, m0
	s_mov_b32 m0, s7
	s_nop 0
	global_load_lds_dwordx4 v221, s[76:77]
	s_mov_b32 m0, vcc_hi
	s_nop 0
	s_mov_b32 vcc_hi, m0
	s_mov_b32 m0, vcc_lo
	s_nop 0
	global_load_lds_dwordx4 v222, s[60:61]
	s_mov_b32 m0, vcc_hi
	s_add_i32 vcc_lo, s7, 0x2000
	s_mov_b32 vcc_hi, m0
	s_mov_b32 m0, vcc_lo
	s_nop 0
	global_load_lds_dwordx4 v223, s[76:77]
	s_mov_b32 m0, vcc_hi
	s_addk_i32 s7, 0x6000
	s_mov_b32 s76, m0
	s_mov_b32 m0, s7
	s_nop 0
	global_load_lds_dwordx4 v224, s[60:61]
	s_mov_b32 m0, s76
	s_add_i32 s7, s68, s97
	s_cmp_ge_u32 s7, s94
	s_cselect_b64 s[60:61], -1, 0
	s_cmp_lt_u32 s7, s95
	s_cselect_b64 s[76:77], -1, 0
	s_and_b64 s[60:61], s[60:61], s[76:77]
	s_andn2_b64 vcc, exec, s[60:61]
	s_add_i32 s7, s68, s97
	s_mov_b32 s100, 0
	s_add_i32 s98, s64, -4
	s_max_i32 s98, s98, 0
	s_min_i32 s98, s98, 0x78
	s_sub_i32 s99, s7, s98
	s_cmp_lt_u32 s99, 8
	s_cselect_b32 s99, 1, 0
	s_or_b32 s100, s100, s99
	s_add_i32 s98, s64, -3
	s_max_i32 s98, s98, 0
	s_min_i32 s98, s98, 0x78
	s_sub_i32 s99, s7, s98
	s_cmp_lt_u32 s99, 8
	s_cselect_b32 s99, 2, 0
	s_or_b32 s100, s100, s99
	s_add_i32 s98, s64, -2
	s_max_i32 s98, s98, 0
	s_min_i32 s98, s98, 0x78
	s_sub_i32 s99, s7, s98
	s_cmp_lt_u32 s99, 8
	s_cselect_b32 s99, 4, 0
	s_or_b32 s100, s100, s99
	s_add_i32 s98, s64, -1
	s_max_i32 s98, s98, 0
	s_min_i32 s98, s98, 0x78
	s_sub_i32 s99, s7, s98
	s_cmp_lt_u32 s99, 8
	s_cselect_b32 s99, 8, 0
	s_or_b32 s100, s100, s99
	s_and_b32 s7, s6, 0x18000
	s_add_i32 s7, s65, s7
	s_add_i32 s7, s7, s32
	v_add_u32_e32 v130, s7, v111
	v_add3_u32 v235, s7, v210, v205
	v_add_u32_e32 v131, v130, v204
	v_add_u32_e32 v130, v130, v203
	s_lshr_b32 s98, s32, 5
	s_lshl_b32 s99, s2, 6
	s_sub_i32 s98, s98, s99
	s_add_i32 s98, s98, 0x1fe8c
	v_add3_u32 v236, v129, v110, s98
	v_mov_b32_e32 v238, 0xf149f2ca
	s_cmp_eq_u32 s100, 15
	s_cbranch_scc1 .Lna2_full
	ds_read_b128 v[160:163], v130
	ds_read_b128 v[164:167], v131
	ds_read_b128 v[168:171], v130 offset:2048
	ds_read_b128 v[172:175], v131 offset:2048
	ds_read2_b32 v[100:101], v236 offset0:201 offset1:202
	ds_read2_b32 v[102:103], v236 offset0:203 offset1:204
	ds_read2_b32 v[104:105], v236 offset0:217 offset1:218
	ds_read2_b32 v[106:107], v236 offset0:219 offset1:220
	ds_read2_b32 v[132:133], v236 offset0:170 offset1:171
	ds_read2_b32 v[134:135], v236 offset0:172 offset1:173
	ds_read2_b32 v[136:137], v236 offset0:186 offset1:187
	ds_read2_b32 v[138:139], v236 offset0:188 offset1:189
	v_add_u32_e32 v232, v235, v206
	v_add_u32_e32 v233, v235, v207
	v_add_u32_e32 v234, v235, v208
	v_add_u32_e32 v235, v235, v209
	s_waitcnt lgkmcnt(4)
	v_cndmask_b32_e64 v100, v238, v100, s[8:9]
	v_cndmask_b32_e64 v101, v238, v101, s[10:11]
	v_cndmask_b32_e64 v102, v238, v102, s[12:13]
	v_cndmask_b32_e64 v103, v238, v103, s[14:15]
	v_cndmask_b32_e64 v104, v238, v104, s[16:17]
	v_cndmask_b32_e64 v105, v238, v105, s[18:19]
	v_cndmask_b32_e64 v106, v238, v106, s[20:21]
	v_cndmask_b32_e64 v107, v238, v107, s[22:23]
	s_bitcmp1_b32 s100, 0
	s_cbranch_scc0 .Lna2_s1
	v_mfma_f32_16x16x32_bf16 v[100:103], v[160:163], v[4:7], v[100:103]
	v_mfma_f32_16x16x32_bf16 v[104:107], v[168:171], v[4:7], v[104:107]
	v_mfma_f32_16x16x32_bf16 v[100:103], v[164:167], v[8:11], v[100:103]
	v_mfma_f32_16x16x32_bf16 v[104:107], v[172:175], v[8:11], v[104:107]
.Lna2_s1:
	ds_read_b64_tr_b16 v[176:177], v232 offset:16384
	ds_read_b64_tr_b16 v[178:179], v232 offset:18432
	ds_read_b64_tr_b16 v[180:181], v233 offset:16384
	ds_read_b64_tr_b16 v[182:183], v233 offset:18432
	ds_read_b64_tr_b16 v[184:185], v234 offset:16384
	ds_read_b64_tr_b16 v[186:187], v234 offset:18432
	ds_read_b64_tr_b16 v[188:189], v235 offset:16384
	ds_read_b64_tr_b16 v[190:191], v235 offset:18432
	s_waitcnt lgkmcnt(8)
	v_cndmask_b32_e64 v132, v238, v132, s[8:9]
	v_cndmask_b32_e64 v133, v238, v133, s[10:11]
	v_cndmask_b32_e64 v134, v238, v134, s[12:13]
	v_cndmask_b32_e64 v135, v238, v135, s[14:15]
	v_cndmask_b32_e64 v136, v238, v136, s[16:17]
	v_cndmask_b32_e64 v137, v238, v137, s[18:19]
	v_cndmask_b32_e64 v138, v238, v138, s[20:21]
	v_cndmask_b32_e64 v139, v238, v139, s[22:23]
	ds_read2_b32 v[140:141], v236 offset0:139 offset1:140
	ds_read2_b32 v[142:143], v236 offset0:141 offset1:142
	ds_read2_b32 v[144:145], v236 offset0:155 offset1:156
	ds_read2_b32 v[146:147], v236 offset0:157 offset1:158
	s_bitcmp1_b32 s100, 1
	s_cbranch_scc0 .Lna2_s2
	v_mfma_f32_16x16x32_bf16 v[132:135], v[160:163], v[12:15], v[132:135]
	v_mfma_f32_16x16x32_bf16 v[136:139], v[168:171], v[12:15], v[136:139]
	v_mfma_f32_16x16x32_bf16 v[132:135], v[164:167], v[16:19], v[132:135]
	v_mfma_f32_16x16x32_bf16 v[136:139], v[172:175], v[16:19], v[136:139]
; #define LAS __attribute__((address_space(3)))
; __device__ __forceinline__ s16x4 vtr(const LAS unsigned char* p) { return __builtin_bit_cast(s16x4, __builtin_amdgcn_ds_read_tr16_b64_v4i16((LAS v4i16_t*)p)); }
; __device__ __forceinline__ bf16x8 cat8(s16x4 a, s16x4 b) { return (bf16x8){a[0], a[1], a[2], a[3], b[0], b[1], b[2], b[3]}; }
; __device__ __forceinline__ bf16x8 pack8(const f32x4& a, const f32x4& b) { u32x4 w; w.x = pkbf(a[0], a[1]); w.y = pkbf(a[2], a[3]); w.z = pkbf(b[0], b[1]); w.w = pkbf(b[2], b[3]); return __builtin_bit_cast(bf16x8, w); }
; __device__ __forceinline__ void na_local_tile(f32x4 (&O)[4][4], float (&ls)[4], const bf16x8 (&qf)[4][2], float negb,
;                                               const LAS unsigned char* Kt, const LAS unsigned char* Vt, int lane, const LAS float* bias_row, bool rowvalid) {
;     ...
; #pragma unroll
;     for (int grp = 0; grp < 4; ++grp) {
;         const int kwin = grp == 0 ? 0 : (grp == 1 ? 8 : (grp == 2 ? 24 : 32));
;         f32x4 S[2];
; #pragma unroll
;         for (int k2 = 0; k2 < 2; ++k2) {
;             const bf16x8 kf0 = *(const LAS bf16x8*)(kb0 + (kwin + 16 * k2) * 128 + kx0), kf1 = *(const LAS bf16x8*)(kb0 + (kwin + 16 * k2) * 128 + kx1);
;             S[k2] = __builtin_amdgcn_mfma_f32_16x16x32_bf16(kf0, qf[grp][0], (f32x4){negb, negb, negb, negb}, 0, 0, 0);
;             S[k2] = __builtin_amdgcn_mfma_f32_16x16x32_bf16(kf1, qf[grp][1], S[k2], 0, 0, 0); }
;         const int c = 16 * grp + l15; const int c0 = rowvalid ? min(max(c - 8, 0), 48) : 4096;
;         const LAS float* bl = bias_row + (15 - c + 4 * g);
; #pragma unroll
;         for (int k2 = 0; k2 < 2; ++k2)
; #pragma unroll
;             for (int i = 0; i < 4; ++i) { const int kc = kwin + 16 * k2 + 4 * g + i; const float bias = bl[kwin + 16 * k2 + i];
;                 S[k2][i] = ((unsigned)(kc - c0) < 16u) ? S[k2][i] + bias : NEGBIG; }
;         ls[grp] += exp_step<2>(S);
;         const bf16x8 pf = pack8(S[0], S[1]);
; #pragma unroll
;         for (int db = 0; db < 4; ++db) {
;             const LAS unsigned char* va = vrow + ((db ^ swz) << 5) + kwin * 128;
;             const bf16x8 vf = cat8(vtr(va), vtr(va + 16 * 128));
;             O[grp][db] = __builtin_amdgcn_mfma_f32_16x16x32_bf16(vf, pf, O[grp][db], 0, 0, 0);
;         }
;         __builtin_amdgcn_sched_barrier(0x108);
.Lna2_s2:
	s_bitcmp1_b32 s100, 0
	s_cbranch_scc0 .Lna2_s3
	v_exp_f32_e32 v100, v100
	v_exp_f32_e32 v101, v101
	v_exp_f32_e32 v102, v102
	v_add_f32_e32 v154, v100, v101
	v_exp_f32_e32 v103, v103
	v_exp_f32_e32 v104, v104
	v_add_f32_e32 v154, v154, v102
	v_exp_f32_e32 v105, v105
	v_add_f32_e32 v154, v154, v103
	v_exp_f32_e32 v106, v106
	v_add_f32_e32 v154, v154, v104
	v_exp_f32_e32 v107, v107
	v_add_f32_e32 v154, v154, v105
	v_cvt_pk_bf16_f32 v100, v100, v101
	v_add_f32_e32 v154, v154, v106
	v_cvt_pk_bf16_f32 v101, v102, v103
	v_cvt_pk_bf16_f32 v102, v104, v105
	v_cvt_pk_bf16_f32 v103, v106, v107
	v_add_f32_e32 v154, v154, v107
	v_add_f32_e32 v126, v126, v154
.Lna2_s3:
	s_waitcnt lgkmcnt(4)
	s_bitcmp1_b32 s100, 0
	s_cbranch_scc0 .Lna2_s4
	v_mfma_f32_16x16x32_bf16 v[48:51], v[176:179], v[100:103], v[48:51]
	v_mfma_f32_16x16x32_bf16 v[44:47], v[180:183], v[100:103], v[44:47]
	v_mfma_f32_16x16x32_bf16 v[40:43], v[184:187], v[100:103], v[40:43]
	v_mfma_f32_16x16x32_bf16 v[36:39], v[188:191], v[100:103], v[36:39]
.Lna2_s4:
	s_waitcnt lgkmcnt(0)
	v_cndmask_b32_e64 v140, v238, v140, s[8:9]
	v_cndmask_b32_e64 v141, v238, v141, s[10:11]
	v_cndmask_b32_e64 v142, v238, v142, s[12:13]
	v_cndmask_b32_e64 v143, v238, v143, s[14:15]
	v_cndmask_b32_e64 v144, v238, v144, s[16:17]
	v_cndmask_b32_e64 v145, v238, v145, s[18:19]
	v_cndmask_b32_e64 v146, v238, v146, s[20:21]
	v_cndmask_b32_e64 v147, v238, v147, s[22:23]
	ds_read2_b32 v[148:149], v236 offset0:108 offset1:109
	ds_read2_b32 v[150:151], v236 offset0:110 offset1:111
	ds_read2_b32 v[228:229], v236 offset0:124 offset1:125
	ds_read2_b32 v[230:231], v236 offset0:126 offset1:127
	s_bitcmp1_b32 s100, 2
	s_cbranch_scc0 .Lna2_s5
	v_mfma_f32_16x16x32_bf16 v[140:143], v[160:163], v[20:23], v[140:143]
	v_mfma_f32_16x16x32_bf16 v[144:147], v[168:171], v[20:23], v[144:147]
	v_mfma_f32_16x16x32_bf16 v[140:143], v[164:167], v[24:27], v[140:143]
	v_mfma_f32_16x16x32_bf16 v[144:147], v[172:175], v[24:27], v[144:147]
.Lna2_s5:
	s_bitcmp1_b32 s100, 1
	s_cbranch_scc0 .Lna2_s6
	v_exp_f32_e32 v132, v132
	v_exp_f32_e32 v133, v133
	v_exp_f32_e32 v134, v134
	v_add_f32_e32 v154, v132, v133
	v_exp_f32_e32 v135, v135
	v_exp_f32_e32 v136, v136
	v_add_f32_e32 v154, v154, v134
	v_exp_f32_e32 v137, v137
	v_add_f32_e32 v154, v154, v135
	v_exp_f32_e32 v138, v138
	v_add_f32_e32 v154, v154, v136
	v_exp_f32_e32 v139, v139
	v_add_f32_e32 v154, v154, v137
	v_cvt_pk_bf16_f32 v132, v132, v133
	v_add_f32_e32 v154, v154, v138
	v_cvt_pk_bf16_f32 v133, v134, v135
	v_cvt_pk_bf16_f32 v134, v136, v137
	v_cvt_pk_bf16_f32 v135, v138, v139
	v_add_f32_e32 v154, v154, v139
	v_add_f32_e32 v127, v127, v154
	v_mfma_f32_16x16x32_bf16 v[64:67], v[176:179], v[132:135], v[64:67]
	v_mfma_f32_16x16x32_bf16 v[60:63], v[180:183], v[132:135], v[60:63]
	v_mfma_f32_16x16x32_bf16 v[56:59], v[184:187], v[132:135], v[56:59]
	v_mfma_f32_16x16x32_bf16 v[52:55], v[188:191], v[132:135], v[52:55]
.Lna2_s6:
	s_waitcnt lgkmcnt(0)
	v_cndmask_b32_e64 v148, v238, v148, s[8:9]
	v_cndmask_b32_e64 v149, v238, v149, s[10:11]
	v_cndmask_b32_e64 v150, v238, v150, s[12:13]
	v_cndmask_b32_e64 v151, v238, v151, s[14:15]
	v_cndmask_b32_e64 v228, v238, v228, s[16:17]
	v_cndmask_b32_e64 v229, v238, v229, s[18:19]
	v_cndmask_b32_e64 v230, v238, v230, s[20:21]
	v_cndmask_b32_e64 v231, v238, v231, s[22:23]
	s_bitcmp1_b32 s100, 3
	s_cbranch_scc0 .Lna2_s7
	v_mfma_f32_16x16x32_bf16 v[148:151], v[160:163], v[28:31], v[148:151]
	v_mfma_f32_16x16x32_bf16 v[228:231], v[168:171], v[28:31], v[228:231]
	v_mfma_f32_16x16x32_bf16 v[148:151], v[164:167], v[32:35], v[148:151]
	v_mfma_f32_16x16x32_bf16 v[228:231], v[172:175], v[32:35], v[228:231]
.Lna2_s7:
	s_bitcmp1_b32 s100, 2
	s_cbranch_scc0 .Lna2_s8
	v_exp_f32_e32 v140, v140
	v_exp_f32_e32 v141, v141
	v_exp_f32_e32 v142, v142
	v_add_f32_e32 v154, v140, v141
	v_exp_f32_e32 v143, v143
	v_exp_f32_e32 v144, v144
	v_add_f32_e32 v154, v154, v142
	v_exp_f32_e32 v145, v145
	v_add_f32_e32 v154, v154, v143
	v_exp_f32_e32 v146, v146
	v_add_f32_e32 v154, v154, v144
	v_exp_f32_e32 v147, v147
	v_add_f32_e32 v154, v154, v145
	v_cvt_pk_bf16_f32 v140, v140, v141
	v_add_f32_e32 v154, v154, v146
	v_cvt_pk_bf16_f32 v141, v142, v143
	v_cvt_pk_bf16_f32 v142, v144, v145
	v_cvt_pk_bf16_f32 v143, v146, v147
	v_add_f32_e32 v154, v154, v147
	v_add_f32_e32 v124, v124, v154
	v_mfma_f32_16x16x32_bf16 v[80:83], v[176:179], v[140:143], v[80:83]
	v_mfma_f32_16x16x32_bf16 v[76:79], v[180:183], v[140:143], v[76:79]
	v_mfma_f32_16x16x32_bf16 v[72:75], v[184:187], v[140:143], v[72:75]
	v_mfma_f32_16x16x32_bf16 v[68:71], v[188:191], v[140:143], v[68:71]
.Lna2_s8:
	s_bitcmp1_b32 s100, 3
	s_cbranch_scc0 .Lna2_s9
	s_nop 6
	v_exp_f32_e32 v148, v148
	v_exp_f32_e32 v149, v149
	v_exp_f32_e32 v150, v150
	v_add_f32_e32 v154, v148, v149
	v_exp_f32_e32 v151, v151
	v_exp_f32_e32 v228, v228
	v_add_f32_e32 v154, v154, v150
	v_exp_f32_e32 v229, v229
	v_add_f32_e32 v154, v154, v151
	v_exp_f32_e32 v230, v230
	v_add_f32_e32 v154, v154, v228
	v_exp_f32_e32 v231, v231
	v_add_f32_e32 v154, v154, v229
	v_cvt_pk_bf16_f32 v148, v148, v149
	v_add_f32_e32 v154, v154, v230
	v_cvt_pk_bf16_f32 v149, v150, v151
	v_cvt_pk_bf16_f32 v150, v228, v229
	v_cvt_pk_bf16_f32 v151, v230, v231
	v_add_f32_e32 v154, v154, v231
	v_add_f32_e32 v125, v125, v154
	v_mfma_f32_16x16x32_bf16 v[84:87], v[176:179], v[148:151], v[84:87]
	v_mfma_f32_16x16x32_bf16 v[92:95], v[180:183], v[148:151], v[92:95]
	v_mfma_f32_16x16x32_bf16 v[88:91], v[184:187], v[148:151], v[88:91]
	v_mfma_f32_16x16x32_bf16 v[96:99], v[188:191], v[148:151], v[96:99]

; #define LAS __attribute__((address_space(3)))
; __device__ __forceinline__ s16x4 vtr(const LAS unsigned char* p) { return __builtin_bit_cast(s16x4, __builtin_amdgcn_ds_read_tr16_b64_v4i16((LAS v4i16_t*)p)); }
; __device__ __forceinline__ bf16x8 cat8(s16x4 a, s16x4 b) { return (bf16x8){a[0], a[1], a[2], a[3], b[0], b[1], b[2], b[3]}; }
; __device__ __forceinline__ bf16x8 pack8(const f32x4& a, const f32x4& b) { u32x4 w; w.x = pkbf(a[0], a[1]); w.y = pkbf(a[2], a[3]); w.z = pkbf(b[0], b[1]); w.w = pkbf(b[2], b[3]); return __builtin_bit_cast(bf16x8, w); }
; __device__ __forceinline__ void na_local_tile(f32x4 (&O)[4][4], float (&ls)[4], const bf16x8 (&qf)[4][2], float negb,
;                                               const LAS unsigned char* Kt, const LAS unsigned char* Vt, int lane, const LAS float* bias_row, bool rowvalid) {
;     ...
; #pragma unroll
;     for (int grp = 0; grp < 4; ++grp) {
;         const int kwin = grp == 0 ? 0 : (grp == 1 ? 8 : (grp == 2 ? 24 : 32));
;         f32x4 S[2];
; #pragma unroll
;         for (int k2 = 0; k2 < 2; ++k2) {
;             const bf16x8 kf0 = *(const LAS bf16x8*)(kb0 + (kwin + 16 * k2) * 128 + kx0), kf1 = *(const LAS bf16x8*)(kb0 + (kwin + 16 * k2) * 128 + kx1);
;             S[k2] = __builtin_amdgcn_mfma_f32_16x16x32_bf16(kf0, qf[grp][0], (f32x4){negb, negb, negb, negb}, 0, 0, 0);
;             S[k2] = __builtin_amdgcn_mfma_f32_16x16x32_bf16(kf1, qf[grp][1], S[k2], 0, 0, 0); }
;         const int c = 16 * grp + l15; const int c0 = rowvalid ? min(max(c - 8, 0), 48) : 4096;
;         const LAS float* bl = bias_row + (15 - c + 4 * g);
; #pragma unroll
;         for (int k2 = 0; k2 < 2; ++k2)
; #pragma unroll
;             for (int i = 0; i < 4; ++i) { const int kc = kwin + 16 * k2 + 4 * g + i; const float bias = bl[kwin + 16 * k2 + i];
;                 S[k2][i] = ((unsigned)(kc - c0) < 16u) ? S[k2][i] + bias : NEGBIG; }
;         ls[grp] += exp_step<2>(S);
;         const bf16x8 pf = pack8(S[0], S[1]);
; #pragma unroll
;         for (int db = 0; db < 4; ++db) {
;             const LAS unsigned char* va = vrow + ((db ^ swz) << 5) + kwin * 128;
;             const bf16x8 vf = cat8(vtr(va), vtr(va + 16 * 128));
;             O[grp][db] = __builtin_amdgcn_mfma_f32_16x16x32_bf16(vf, pf, O[grp][db], 0, 0, 0);
;         }
;         __builtin_amdgcn_sched_barrier(0x108);
.Lna2_full:
	ds_read_b128 v[160:163], v130
	ds_read_b128 v[164:167], v131
	ds_read_b128 v[168:171], v130 offset:2048
	ds_read_b128 v[172:175], v131 offset:2048
	ds_read2_b32 v[100:101], v236 offset0:201 offset1:202
	ds_read2_b32 v[102:103], v236 offset0:203 offset1:204
	ds_read2_b32 v[104:105], v236 offset0:217 offset1:218
	ds_read2_b32 v[106:107], v236 offset0:219 offset1:220
	ds_read2_b32 v[132:133], v236 offset0:170 offset1:171
	ds_read2_b32 v[134:135], v236 offset0:172 offset1:173
	ds_read2_b32 v[136:137], v236 offset0:186 offset1:187
	ds_read2_b32 v[138:139], v236 offset0:188 offset1:189
	v_add_u32_e32 v232, v235, v206
	v_add_u32_e32 v233, v235, v207
	v_add_u32_e32 v234, v235, v208
	v_add_u32_e32 v235, v235, v209
	s_waitcnt lgkmcnt(4)
	v_cndmask_b32_e64 v100, v238, v100, s[8:9]
	v_cndmask_b32_e64 v101, v238, v101, s[10:11]
	v_cndmask_b32_e64 v102, v238, v102, s[12:13]
	v_cndmask_b32_e64 v103, v238, v103, s[14:15]
	v_cndmask_b32_e64 v104, v238, v104, s[16:17]
	v_cndmask_b32_e64 v105, v238, v105, s[18:19]
	v_cndmask_b32_e64 v106, v238, v106, s[20:21]
	v_cndmask_b32_e64 v107, v238, v107, s[22:23]
	v_mfma_f32_16x16x32_bf16 v[100:103], v[160:163], v[4:7], v[100:103]
	v_mfma_f32_16x16x32_bf16 v[104:107], v[168:171], v[4:7], v[104:107]
	v_mfma_f32_16x16x32_bf16 v[100:103], v[164:167], v[8:11], v[100:103]
	v_mfma_f32_16x16x32_bf16 v[104:107], v[172:175], v[8:11], v[104:107]
	ds_read_b64_tr_b16 v[176:177], v232 offset:16384
	ds_read_b64_tr_b16 v[178:179], v232 offset:18432
	ds_read_b64_tr_b16 v[180:181], v233 offset:16384
	ds_read_b64_tr_b16 v[182:183], v233 offset:18432
	ds_read_b64_tr_b16 v[184:185], v234 offset:16384
	ds_read_b64_tr_b16 v[186:187], v234 offset:18432
	ds_read_b64_tr_b16 v[188:189], v235 offset:16384
	ds_read_b64_tr_b16 v[190:191], v235 offset:18432
	s_waitcnt lgkmcnt(8)
	v_cndmask_b32_e64 v132, v238, v132, s[8:9]
	v_cndmask_b32_e64 v133, v238, v133, s[10:11]
	v_cndmask_b32_e64 v134, v238, v134, s[12:13]
	v_cndmask_b32_e64 v135, v238, v135, s[14:15]
	v_cndmask_b32_e64 v136, v238, v136, s[16:17]
	v_cndmask_b32_e64 v137, v238, v137, s[18:19]
	v_cndmask_b32_e64 v138, v238, v138, s[20:21]
	v_cndmask_b32_e64 v139, v238, v139, s[22:23]
	ds_read2_b32 v[140:141], v236 offset0:139 offset1:140
	ds_read2_b32 v[142:143], v236 offset0:141 offset1:142
	ds_read2_b32 v[144:145], v236 offset0:155 offset1:156
	ds_read2_b32 v[146:147], v236 offset0:157 offset1:158
	v_mfma_f32_16x16x32_bf16 v[132:135], v[160:163], v[12:15], v[132:135]
	v_mfma_f32_16x16x32_bf16 v[136:139], v[168:171], v[12:15], v[136:139]
	v_mfma_f32_16x16x32_bf16 v[132:135], v[164:167], v[16:19], v[132:135]
	v_mfma_f32_16x16x32_bf16 v[136:139], v[172:175], v[16:19], v[136:139]
	v_exp_f32_e32 v100, v100
	v_exp_f32_e32 v101, v101
	v_exp_f32_e32 v102, v102
	v_add_f32_e32 v154, v100, v101
	v_exp_f32_e32 v103, v103
	v_exp_f32_e32 v104, v104
	v_add_f32_e32 v154, v154, v102
	v_exp_f32_e32 v105, v105
	v_add_f32_e32 v154, v154, v103
	v_exp_f32_e32 v106, v106
	v_add_f32_e32 v154, v154, v104
	v_exp_f32_e32 v107, v107
	v_add_f32_e32 v154, v154, v105
	v_cvt_pk_bf16_f32 v100, v100, v101
	v_add_f32_e32 v154, v154, v106
	v_cvt_pk_bf16_f32 v101, v102, v103
	v_cvt_pk_bf16_f32 v102, v104, v105
	v_cvt_pk_bf16_f32 v103, v106, v107
	v_add_f32_e32 v154, v154, v107
	v_add_f32_e32 v126, v126, v154
	s_waitcnt lgkmcnt(4)
	v_mfma_f32_16x16x32_bf16 v[48:51], v[176:179], v[100:103], v[48:51]
	v_mfma_f32_16x16x32_bf16 v[44:47], v[180:183], v[100:103], v[44:47]
	v_mfma_f32_16x16x32_bf16 v[40:43], v[184:187], v[100:103], v[40:43]
	v_mfma_f32_16x16x32_bf16 v[36:39], v[188:191], v[100:103], v[36:39]
	s_waitcnt lgkmcnt(0)
; #define LAS __attribute__((address_space(3)))
; __device__ __forceinline__ s16x4 vtr(const LAS unsigned char* p) { return __builtin_bit_cast(s16x4, __builtin_amdgcn_ds_read_tr16_b64_v4i16((LAS v4i16_t*)p)); }
; __device__ __forceinline__ bf16x8 cat8(s16x4 a, s16x4 b) { return (bf16x8){a[0], a[1], a[2], a[3], b[0], b[1], b[2], b[3]}; }
; __device__ __forceinline__ bf16x8 pack8(const f32x4& a, const f32x4& b) { u32x4 w; w.x = pkbf(a[0], a[1]); w.y = pkbf(a[2], a[3]); w.z = pkbf(b[0], b[1]); w.w = pkbf(b[2], b[3]); return __builtin_bit_cast(bf16x8, w); }
; __device__ __forceinline__ void na_local_tile(f32x4 (&O)[4][4], float (&ls)[4], const bf16x8 (&qf)[4][2], float negb,
;                                               const LAS unsigned char* Kt, const LAS unsigned char* Vt, int lane, const LAS float* bias_row, bool rowvalid) {
;     ...
; #pragma unroll
;     for (int grp = 0; grp < 4; ++grp) {
;         const int kwin = grp == 0 ? 0 : (grp == 1 ? 8 : (grp == 2 ? 24 : 32));
;         f32x4 S[2];
; #pragma unroll
;         for (int k2 = 0; k2 < 2; ++k2) {
;             const bf16x8 kf0 = *(const LAS bf16x8*)(kb0 + (kwin + 16 * k2) * 128 + kx0), kf1 = *(const LAS bf16x8*)(kb0 + (kwin + 16 * k2) * 128 + kx1);
;             S[k2] = __builtin_amdgcn_mfma_f32_16x16x32_bf16(kf0, qf[grp][0], (f32x4){negb, negb, negb, negb}, 0, 0, 0);
;             S[k2] = __builtin_amdgcn_mfma_f32_16x16x32_bf16(kf1, qf[grp][1], S[k2], 0, 0, 0); }
;         const int c = 16 * grp + l15; const int c0 = rowvalid ? min(max(c - 8, 0), 48) : 4096;
;         const LAS float* bl = bias_row + (15 - c + 4 * g);
; #pragma unroll
;         for (int k2 = 0; k2 < 2; ++k2)
; #pragma unroll
;             for (int i = 0; i < 4; ++i) { const int kc = kwin + 16 * k2 + 4 * g + i; const float bias = bl[kwin + 16 * k2 + i];
;                 S[k2][i] = ((unsigned)(kc - c0) < 16u) ? S[k2][i] + bias : NEGBIG; }
;         ls[grp] += exp_step<2>(S);
;         const bf16x8 pf = pack8(S[0], S[1]);
; #pragma unroll
;         for (int db = 0; db < 4; ++db) {
;             const LAS unsigned char* va = vrow + ((db ^ swz) << 5) + kwin * 128;
;             const bf16x8 vf = cat8(vtr(va), vtr(va + 16 * 128));
;             O[grp][db] = __builtin_amdgcn_mfma_f32_16x16x32_bf16(vf, pf, O[grp][db], 0, 0, 0);
;         }
;         __builtin_amdgcn_sched_barrier(0x108);
	v_cndmask_b32_e64 v140, v238, v140, s[8:9]
	v_cndmask_b32_e64 v141, v238, v141, s[10:11]
	v_cndmask_b32_e64 v142, v238, v142, s[12:13]
	v_cndmask_b32_e64 v143, v238, v143, s[14:15]
	v_cndmask_b32_e64 v144, v238, v144, s[16:17]
	v_cndmask_b32_e64 v145, v238, v145, s[18:19]
	v_cndmask_b32_e64 v146, v238, v146, s[20:21]
	v_cndmask_b32_e64 v147, v238, v147, s[22:23]
	ds_read2_b32 v[148:149], v236 offset0:108 offset1:109
	ds_read2_b32 v[150:151], v236 offset0:110 offset1:111
	ds_read2_b32 v[228:229], v236 offset0:124 offset1:125
	ds_read2_b32 v[230:231], v236 offset0:126 offset1:127
	v_mfma_f32_16x16x32_bf16 v[140:143], v[160:163], v[20:23], v[140:143]
	v_mfma_f32_16x16x32_bf16 v[144:147], v[168:171], v[20:23], v[144:147]
	v_mfma_f32_16x16x32_bf16 v[140:143], v[164:167], v[24:27], v[140:143]
	v_mfma_f32_16x16x32_bf16 v[144:147], v[172:175], v[24:27], v[144:147]
	v_exp_f32_e32 v132, v132
	v_exp_f32_e32 v133, v133
	v_exp_f32_e32 v134, v134
	v_add_f32_e32 v154, v132, v133
	v_exp_f32_e32 v135, v135
	v_exp_f32_e32 v136, v136
	v_add_f32_e32 v154, v154, v134
	v_exp_f32_e32 v137, v137
	v_add_f32_e32 v154, v154, v135
	v_exp_f32_e32 v138, v138
	v_add_f32_e32 v154, v154, v136
	v_exp_f32_e32 v139, v139
	v_add_f32_e32 v154, v154, v137
	v_cvt_pk_bf16_f32 v132, v132, v133
	v_add_f32_e32 v154, v154, v138
	v_cvt_pk_bf16_f32 v133, v134, v135
	v_cvt_pk_bf16_f32 v134, v136, v137
	v_cvt_pk_bf16_f32 v135, v138, v139
	v_add_f32_e32 v154, v154, v139
	v_add_f32_e32 v127, v127, v154
	v_mfma_f32_16x16x32_bf16 v[64:67], v[176:179], v[132:135], v[64:67]
	v_mfma_f32_16x16x32_bf16 v[60:63], v[180:183], v[132:135], v[60:63]
	v_mfma_f32_16x16x32_bf16 v[56:59], v[184:187], v[132:135], v[56:59]
	v_mfma_f32_16x16x32_bf16 v[52:55], v[188:191], v[132:135], v[52:55]
	s_waitcnt lgkmcnt(0)
	v_cndmask_b32_e64 v148, v238, v148, s[8:9]
	v_cndmask_b32_e64 v149, v238, v149, s[10:11]
	v_cndmask_b32_e64 v150, v238, v150, s[12:13]
	v_cndmask_b32_e64 v151, v238, v151, s[14:15]
	v_cndmask_b32_e64 v228, v238, v228, s[16:17]
	v_cndmask_b32_e64 v229, v238, v229, s[18:19]
	v_cndmask_b32_e64 v230, v238, v230, s[20:21]
	v_cndmask_b32_e64 v231, v238, v231, s[22:23]
	v_mfma_f32_16x16x32_bf16 v[148:151], v[160:163], v[28:31], v[148:151]
	v_mfma_f32_16x16x32_bf16 v[228:231], v[168:171], v[28:31], v[228:231]
	v_mfma_f32_16x16x32_bf16 v[148:151], v[164:167], v[32:35], v[148:151]
	v_mfma_f32_16x16x32_bf16 v[228:231], v[172:175], v[32:35], v[228:231]
	v_exp_f32_e32 v140, v140
	v_exp_f32_e32 v141, v141
	v_exp_f32_e32 v142, v142
	v_add_f32_e32 v154, v140, v141
	v_exp_f32_e32 v143, v143
	v_exp_f32_e32 v144, v144
	v_add_f32_e32 v154, v154, v142
	v_exp_f32_e32 v145, v145
	v_add_f32_e32 v154, v154, v143
	v_exp_f32_e32 v146, v146
	v_add_f32_e32 v154, v154, v144
	v_exp_f32_e32 v147, v147
	v_add_f32_e32 v154, v154, v145
	v_cvt_pk_bf16_f32 v140, v140, v141
	v_add_f32_e32 v154, v154, v146
	v_cvt_pk_bf16_f32 v141, v142, v143
	v_cvt_pk_bf16_f32 v142, v144, v145
	v_cvt_pk_bf16_f32 v143, v146, v147
	v_add_f32_e32 v154, v154, v147
	v_add_f32_e32 v124, v124, v154
	v_mfma_f32_16x16x32_bf16 v[80:83], v[176:179], v[140:143], v[80:83]
	v_mfma_f32_16x16x32_bf16 v[76:79], v[180:183], v[140:143], v[76:79]
	v_mfma_f32_16x16x32_bf16 v[72:75], v[184:187], v[140:143], v[72:75]
	v_mfma_f32_16x16x32_bf16 v[68:71], v[188:191], v[140:143], v[68:71]
	v_exp_f32_e32 v148, v148
	v_exp_f32_e32 v149, v149
	v_exp_f32_e32 v150, v150
	v_add_f32_e32 v154, v148, v149
	v_exp_f32_e32 v151, v151
	v_exp_f32_e32 v228, v228
	v_add_f32_e32 v154, v154, v150
	v_exp_f32_e32 v229, v229
	v_add_f32_e32 v154, v154, v151
	v_exp_f32_e32 v230, v230
	v_add_f32_e32 v154, v154, v228
	v_exp_f32_e32 v231, v231
	v_add_f32_e32 v154, v154, v229
	v_cvt_pk_bf16_f32 v148, v148, v149
	v_add_f32_e32 v154, v154, v230
	v_cvt_pk_bf16_f32 v149, v150, v151
	v_cvt_pk_bf16_f32 v150, v228, v229
	v_cvt_pk_bf16_f32 v151, v230, v231
	v_add_f32_e32 v154, v154, v231
	v_add_f32_e32 v125, v125, v154
	v_mfma_f32_16x16x32_bf16 v[84:87], v[176:179], v[148:151], v[84:87]
	v_mfma_f32_16x16x32_bf16 v[92:95], v[180:183], v[148:151], v[92:95]
	v_mfma_f32_16x16x32_bf16 v[88:91], v[184:187], v[148:151], v[88:91]
	v_mfma_f32_16x16x32_bf16 v[96:99], v[188:191], v[148:151], v[96:99]
	s_branch .LBB0_382
